# a20: GEMM priority segment extended: raised from the k-tile barrier until after the first MFMA group of the next k-tile
# speedup vs baseline: 1.0262x; 1.0022x over previous
; #define GBAR() do { asm volatile("s_waitcnt vmcnt(0) lgkmcnt(0)" ::: "memory"); __builtin_amdgcn_s_barrier(); } while (0)
; template <int EPI, bool GUARD>
; DEVI void gemm_tile(const Params& p, const bf16_t* __restrict__ A, int lda, const bf16_t* __restrict__ Bt, int ldb, int K,
;                           int row_base, int row_lo, int row_hi, int tile_n, int layer, int which, char* lds) {
;     ...
;   const int swz = c16 >> 1;
;   int koff[2];
; #pragma unroll
;   for (int ks = 0; ks < 2; ++ks) koff[ks] = ((ks * 4 + q4) ^ swz) << 4;
;   const int arow = (wr * 64 + c16) * 128, brow = 16384 + (wc * 64 + c16) * 128;
;     ...
;   GISSUE(0, 0); GBAR();
;   for (int k0 = 0; k0 < K; k0 += 128) {
;     GISSUE(k0 + 64, 1);
;     KSTEPS(0);
;     GBAR();
;     if (k0 + 128 < K) GISSUE(k0 + 128, 0);
;     KSTEPS(1);
;     GBAR();
;   }
.LBB0_536:
	ds_read_b128 v[82:85], v64 offset:32768
	ds_read_b128 v[86:89], v105 offset:49152
	ds_read_b128 v[90:93], v64 offset:34816
	ds_read_b128 v[94:97], v105 offset:51200
	ds_read_b128 v[108:111], v105 offset:53248
	ds_read_b128 v[112:115], v105 offset:55296
	s_addk_i32 s61, 0x80
	s_waitcnt lgkmcnt(0)
	v_mfma_f32_16x16x32_bf16 v[0:3], v[82:85], v[86:89], v[0:3]
	s_add_u32 s16, s16, 0x100
	s_addc_u32 s17, s17, 0
	s_andn2_b64 vcc, exec, s[18:19]
	v_mfma_f32_16x16x32_bf16 v[4:7], v[82:85], v[94:97], v[4:7]
	v_mfma_f32_16x16x32_bf16 v[8:11], v[82:85], v[108:111], v[8:11]
	v_mfma_f32_16x16x32_bf16 v[12:15], v[82:85], v[112:115], v[12:15]
	v_mfma_f32_16x16x32_bf16 v[16:19], v[90:93], v[86:89], v[16:19]
	v_mfma_f32_16x16x32_bf16 v[20:23], v[90:93], v[94:97], v[20:23]
	v_mfma_f32_16x16x32_bf16 v[24:27], v[90:93], v[108:111], v[24:27]
	v_mfma_f32_16x16x32_bf16 v[28:31], v[90:93], v[112:115], v[28:31]
	s_setprio 0
	ds_read_b128 v[82:85], v64 offset:36864
	ds_read_b128 v[90:93], v64 offset:38912
	s_waitcnt lgkmcnt(0)
	v_mfma_f32_16x16x32_bf16 v[116:119], v[82:85], v[86:89], v[32:35]
	s_nop 2
	ds_read_b128 v[32:35], v106 offset:32768
	v_mfma_f32_16x16x32_bf16 v[120:123], v[82:85], v[94:97], v[36:39]
	v_mfma_f32_16x16x32_bf16 v[124:127], v[82:85], v[108:111], v[40:43]
	v_mfma_f32_16x16x32_bf16 v[82:85], v[82:85], v[112:115], v[44:47]
	v_mfma_f32_16x16x32_bf16 v[86:89], v[90:93], v[86:89], v[48:51]
	v_mfma_f32_16x16x32_bf16 v[94:97], v[90:93], v[94:97], v[52:55]
	v_mfma_f32_16x16x32_bf16 v[108:111], v[90:93], v[108:111], v[56:59]
	v_mfma_f32_16x16x32_bf16 v[90:93], v[90:93], v[112:115], v[60:63]
	ds_read_b128 v[112:115], v107 offset:49152
	ds_read_b128 v[36:39], v106 offset:34816
	ds_read_b128 v[128:131], v107 offset:51200
	ds_read_b128 v[132:135], v107 offset:53248
	ds_read_b128 v[136:139], v107 offset:55296
	s_waitcnt lgkmcnt(0)
	v_mfma_f32_16x16x32_bf16 v[56:59], v[32:35], v[112:115], v[0:3]
	v_mfma_f32_16x16x32_bf16 v[60:63], v[32:35], v[132:135], v[8:11]
	s_nop 1
	ds_read_b128 v[0:3], v106 offset:36864
	ds_read_b128 v[8:11], v106 offset:38912
	s_waitcnt vmcnt(0) lgkmcnt(0)
	s_barrier
	s_cbranch_vccz .Lge0_exit1
	s_setprio 1
	v_mfma_f32_16x16x32_bf16 v[48:51], v[32:35], v[128:131], v[4:7]
	s_add_i32 m0, s45, 0x8000
	v_lshl_add_u64 v[246:247], s[16:17], 0, v[66:67]
	v_lshl_add_u64 v[246:247], v[246:247], 0, s[4:5]
	global_load_lds_dwordx4 v[246:247], off
	v_mfma_f32_16x16x32_bf16 v[52:55], v[32:35], v[136:139], v[12:15]
	s_add_i32 m0, s45, 0xc000
	v_lshl_add_u64 v[246:247], s[16:17], 0, v[74:75]
	v_lshl_add_u64 v[246:247], v[246:247], 0, s[6:7]
	global_load_lds_dwordx4 v[246:247], off
	v_mfma_f32_16x16x32_bf16 v[40:43], v[36:39], v[112:115], v[16:19]
	s_add_i32 m0, s45, 0x8400
	v_lshl_add_u64 v[246:247], s[16:17], 0, v[68:69]
	v_lshl_add_u64 v[246:247], v[246:247], 0, s[4:5]
	global_load_lds_dwordx4 v[246:247], off
	v_mfma_f32_16x16x32_bf16 v[32:35], v[36:39], v[128:131], v[20:23]
	s_add_i32 m0, s45, 0xc400
	v_lshl_add_u64 v[246:247], s[16:17], 0, v[76:77]
	v_lshl_add_u64 v[246:247], v[246:247], 0, s[6:7]
	global_load_lds_dwordx4 v[246:247], off
	v_mfma_f32_16x16x32_bf16 v[44:47], v[36:39], v[132:135], v[24:27]
	s_add_i32 m0, s45, 0x8800
	v_lshl_add_u64 v[246:247], s[16:17], 0, v[70:71]
	v_lshl_add_u64 v[246:247], v[246:247], 0, s[4:5]
	global_load_lds_dwordx4 v[246:247], off
	v_mfma_f32_16x16x32_bf16 v[36:39], v[36:39], v[136:139], v[28:31]
	s_add_i32 m0, s45, 0xc800
	v_lshl_add_u64 v[246:247], s[16:17], 0, v[78:79]
	v_lshl_add_u64 v[246:247], v[246:247], 0, s[6:7]
	global_load_lds_dwordx4 v[246:247], off
	s_waitcnt lgkmcnt(0)
	v_mfma_f32_16x16x32_bf16 v[24:27], v[0:3], v[112:115], v[116:119]
	s_add_i32 m0, s45, 0x8c00
	v_lshl_add_u64 v[246:247], s[16:17], 0, v[72:73]
	v_lshl_add_u64 v[246:247], v[246:247], 0, s[4:5]
	global_load_lds_dwordx4 v[246:247], off
	v_mfma_f32_16x16x32_bf16 v[16:19], v[0:3], v[128:131], v[120:123]
	s_add_i32 m0, s45, 0xcc00
	v_lshl_add_u64 v[246:247], s[16:17], 0, v[80:81]
	v_lshl_add_u64 v[246:247], v[246:247], 0, s[6:7]
	global_load_lds_dwordx4 v[246:247], off
	v_mfma_f32_16x16x32_bf16 v[28:31], v[0:3], v[132:135], v[124:127]
	v_mfma_f32_16x16x32_bf16 v[20:23], v[0:3], v[136:139], v[82:85]
	v_mfma_f32_16x16x32_bf16 v[4:7], v[8:11], v[112:115], v[86:89]
	v_mfma_f32_16x16x32_bf16 v[0:3], v[8:11], v[128:131], v[94:97]
	v_mfma_f32_16x16x32_bf16 v[12:15], v[8:11], v[132:135], v[108:111]
	v_mfma_f32_16x16x32_bf16 v[8:11], v[8:11], v[136:139], v[90:93]
	s_cmpk_gt_u32 s61, 0x37f
	s_branch .Lge0_k0

; #define GBAR() do { asm volatile("s_waitcnt vmcnt(0) lgkmcnt(0)" ::: "memory"); __builtin_amdgcn_s_barrier(); } while (0)
; template <int EPI, bool GUARD>
; DEVI void gemm_tile(const Params& p, const bf16_t* __restrict__ A, int lda, const bf16_t* __restrict__ Bt, int ldb, int K,
;                           int row_base, int row_lo, int row_hi, int tile_n, int layer, int which, char* lds) {
;     ...
;   const int swz = c16 >> 1;
;   int koff[2];
; #pragma unroll
;   for (int ks = 0; ks < 2; ++ks) koff[ks] = ((ks * 4 + q4) ^ swz) << 4;
;   const int arow = (wr * 64 + c16) * 128, brow = 16384 + (wc * 64 + c16) * 128;
;     ...
;   GISSUE(0, 0); GBAR();
;   for (int k0 = 0; k0 < K; k0 += 128) {
;     GISSUE(k0 + 64, 1);
;     KSTEPS(0);
;     GBAR();
;     if (k0 + 128 < K) GISSUE(k0 + 128, 0);
;     KSTEPS(1);
;     GBAR();
;   }
.Lge0_k0:
	ds_read_b128 v[108:111], v64
	ds_read_b128 v[112:115], v105 offset:16384
	ds_read_b128 v[116:119], v64 offset:2048
	ds_read_b128 v[120:123], v105 offset:18432
	ds_read_b128 v[124:127], v105 offset:20480
	ds_read_b128 v[128:131], v105 offset:22528
	s_waitcnt lgkmcnt(0)
	v_mfma_f32_16x16x32_bf16 v[56:59], v[108:111], v[112:115], v[56:59]
	s_cselect_b64 s[18:19], -1, 0
	s_and_b64 vcc, exec, s[18:19]
	v_mfma_f32_16x16x32_bf16 v[48:51], v[108:111], v[120:123], v[48:51]
	v_mfma_f32_16x16x32_bf16 v[60:63], v[108:111], v[124:127], v[60:63]
	v_mfma_f32_16x16x32_bf16 v[52:55], v[108:111], v[128:131], v[52:55]
	v_mfma_f32_16x16x32_bf16 v[40:43], v[116:119], v[112:115], v[40:43]
	v_mfma_f32_16x16x32_bf16 v[32:35], v[116:119], v[120:123], v[32:35]
	v_mfma_f32_16x16x32_bf16 v[44:47], v[116:119], v[124:127], v[44:47]
	v_mfma_f32_16x16x32_bf16 v[36:39], v[116:119], v[128:131], v[36:39]
	s_setprio 0
	ds_read_b128 v[108:111], v64 offset:4096
	ds_read_b128 v[116:119], v64 offset:6144
	s_waitcnt lgkmcnt(0)
	v_mfma_f32_16x16x32_bf16 v[140:143], v[108:111], v[124:127], v[28:31]
	v_mfma_f32_16x16x32_bf16 v[124:127], v[116:119], v[124:127], v[12:15]
	s_nop 2
	ds_read_b128 v[12:15], v106
	v_mfma_f32_16x16x32_bf16 v[132:135], v[108:111], v[112:115], v[24:27]
	v_mfma_f32_16x16x32_bf16 v[136:139], v[108:111], v[120:123], v[16:19]
	v_mfma_f32_16x16x32_bf16 v[108:111], v[108:111], v[128:131], v[20:23]
	v_mfma_f32_16x16x32_bf16 v[112:115], v[116:119], v[112:115], v[4:7]
	v_mfma_f32_16x16x32_bf16 v[120:123], v[116:119], v[120:123], v[0:3]
	v_mfma_f32_16x16x32_bf16 v[116:119], v[116:119], v[128:131], v[8:11]
	ds_read_b128 v[128:131], v107 offset:16384
	ds_read_b128 v[28:31], v106 offset:2048
	ds_read_b128 v[144:147], v107 offset:18432
	s_waitcnt lgkmcnt(0)
	v_mfma_f32_16x16x32_bf16 v[0:3], v[12:15], v[128:131], v[56:59]
	s_nop 2
	ds_read_b128 v[56:59], v107 offset:20480
	ds_read_b128 v[148:151], v107 offset:22528
	s_waitcnt lgkmcnt(0)
	v_mfma_f32_16x16x32_bf16 v[8:11], v[12:15], v[56:59], v[60:63]
	v_mfma_f32_16x16x32_bf16 v[24:27], v[28:31], v[56:59], v[44:47]
	s_nop 2
	ds_read_b128 v[44:47], v106 offset:4096
	ds_read_b128 v[60:63], v106 offset:6144
	s_waitcnt vmcnt(0) lgkmcnt(0)
	s_barrier
	s_cbranch_vccnz .Lge0_last0
	s_setprio 1
	v_mfma_f32_16x16x32_bf16 v[4:7], v[12:15], v[144:147], v[48:51]
	s_mov_b32 m0, s45
	v_lshl_add_u64 v[246:247], s[16:17], 0, v[66:67]
	v_lshl_add_u64 v[246:247], v[246:247], 0, s[8:9]
	global_load_lds_dwordx4 v[246:247], off
	v_mfma_f32_16x16x32_bf16 v[12:15], v[12:15], v[148:151], v[52:55]
	s_mov_b32 m0, s46
	v_lshl_add_u64 v[246:247], s[16:17], 0, v[74:75]
	v_lshl_add_u64 v[246:247], v[246:247], 0, s[12:13]
	global_load_lds_dwordx4 v[246:247], off
	v_mfma_f32_16x16x32_bf16 v[16:19], v[28:31], v[128:131], v[40:43]
	s_mov_b32 m0, s47
	v_lshl_add_u64 v[246:247], s[16:17], 0, v[68:69]
	v_lshl_add_u64 v[246:247], v[246:247], 0, s[8:9]
	global_load_lds_dwordx4 v[246:247], off
	v_mfma_f32_16x16x32_bf16 v[20:23], v[28:31], v[144:147], v[32:35]
	s_mov_b32 m0, s54
	v_lshl_add_u64 v[246:247], s[16:17], 0, v[76:77]
	v_lshl_add_u64 v[246:247], v[246:247], 0, s[12:13]
	global_load_lds_dwordx4 v[246:247], off
	v_mfma_f32_16x16x32_bf16 v[28:31], v[28:31], v[148:151], v[36:39]
	s_mov_b32 m0, s55
	v_lshl_add_u64 v[246:247], s[16:17], 0, v[70:71]
	v_lshl_add_u64 v[246:247], v[246:247], 0, s[8:9]
	global_load_lds_dwordx4 v[246:247], off
	s_waitcnt lgkmcnt(0)
	v_mfma_f32_16x16x32_bf16 v[32:35], v[44:47], v[128:131], v[132:135]
	s_mov_b32 m0, s58
	v_lshl_add_u64 v[246:247], s[16:17], 0, v[78:79]
	v_lshl_add_u64 v[246:247], v[246:247], 0, s[12:13]
	global_load_lds_dwordx4 v[246:247], off
	v_mfma_f32_16x16x32_bf16 v[36:39], v[44:47], v[144:147], v[136:139]
	s_mov_b32 m0, s59
	v_lshl_add_u64 v[246:247], s[16:17], 0, v[72:73]
	v_lshl_add_u64 v[246:247], v[246:247], 0, s[8:9]
	global_load_lds_dwordx4 v[246:247], off
	v_mfma_f32_16x16x32_bf16 v[40:43], v[44:47], v[56:59], v[140:143]
	s_mov_b32 m0, s60
	v_lshl_add_u64 v[246:247], s[16:17], 0, v[80:81]
	v_lshl_add_u64 v[246:247], v[246:247], 0, s[12:13]
	global_load_lds_dwordx4 v[246:247], off
	v_mfma_f32_16x16x32_bf16 v[44:47], v[44:47], v[148:151], v[108:111]
	v_mfma_f32_16x16x32_bf16 v[48:51], v[60:63], v[128:131], v[112:115]
	v_mfma_f32_16x16x32_bf16 v[52:55], v[60:63], v[144:147], v[120:123]
	v_mfma_f32_16x16x32_bf16 v[56:59], v[60:63], v[56:59], v[124:127]
	v_mfma_f32_16x16x32_bf16 v[60:63], v[60:63], v[148:151], v[116:119]
	s_branch .LBB0_536

; #define GBAR() do { asm volatile("s_waitcnt vmcnt(0) lgkmcnt(0)" ::: "memory"); __builtin_amdgcn_s_barrier(); } while (0)
; template <int EPI, bool GUARD>
; DEVI void gemm_tile(const Params& p, const bf16_t* __restrict__ A, int lda, const bf16_t* __restrict__ Bt, int ldb, int K,
;                           int row_base, int row_lo, int row_hi, int tile_n, int layer, int which, char* lds) {
;     ...
;   const int swz = c16 >> 1;
;   int koff[2];
; #pragma unroll
;   for (int ks = 0; ks < 2; ++ks) koff[ks] = ((ks * 4 + q4) ^ swz) << 4;
;   const int arow = (wr * 64 + c16) * 128, brow = 16384 + (wc * 64 + c16) * 128;
;     ...
;   GISSUE(0, 0); GBAR();
;   for (int k0 = 0; k0 < K; k0 += 128) {
;     GISSUE(k0 + 64, 1);
;     KSTEPS(0);
;     GBAR();
;     if (k0 + 128 < K) GISSUE(k0 + 128, 0);
;     KSTEPS(1);
;     GBAR();
;   }
.LBB0_667:
	ds_read_b128 v[82:85], v64 offset:32768
	ds_read_b128 v[86:89], v111 offset:49152
	ds_read_b128 v[90:93], v64 offset:34816
	ds_read_b128 v[94:97], v111 offset:51200
	ds_read_b128 v[114:117], v111 offset:53248
	ds_read_b128 v[118:121], v111 offset:55296
	s_addk_i32 s9, 0x80
	s_waitcnt lgkmcnt(0)
	v_mfma_f32_16x16x32_bf16 v[0:3], v[82:85], v[86:89], v[0:3]
	s_add_u32 s4, s4, 0x100
	s_addc_u32 s5, s5, 0
	s_and_b64 vcc, exec, s[6:7]
	v_mfma_f32_16x16x32_bf16 v[4:7], v[82:85], v[94:97], v[4:7]
	v_mfma_f32_16x16x32_bf16 v[8:11], v[82:85], v[114:117], v[8:11]
	v_mfma_f32_16x16x32_bf16 v[12:15], v[82:85], v[118:121], v[12:15]
	v_mfma_f32_16x16x32_bf16 v[82:85], v[90:93], v[86:89], v[16:19]
	v_mfma_f32_16x16x32_bf16 v[20:23], v[90:93], v[94:97], v[20:23]
	v_mfma_f32_16x16x32_bf16 v[24:27], v[90:93], v[114:117], v[24:27]
	v_mfma_f32_16x16x32_bf16 v[28:31], v[90:93], v[118:121], v[28:31]
	s_setprio 0
	ds_read_b128 v[16:19], v64 offset:36864
	ds_read_b128 v[90:93], v64 offset:38912
	s_waitcnt lgkmcnt(0)
	v_mfma_f32_16x16x32_bf16 v[122:125], v[16:19], v[86:89], v[32:35]
	v_mfma_f32_16x16x32_bf16 v[36:39], v[16:19], v[94:97], v[36:39]
	v_mfma_f32_16x16x32_bf16 v[40:43], v[16:19], v[114:117], v[40:43]
	v_mfma_f32_16x16x32_bf16 v[44:47], v[16:19], v[118:121], v[44:47]
	ds_read_b128 v[16:19], v112 offset:32768
	v_mfma_f32_16x16x32_bf16 v[86:89], v[90:93], v[86:89], v[48:51]
	v_mfma_f32_16x16x32_bf16 v[52:55], v[90:93], v[94:97], v[52:55]
	v_mfma_f32_16x16x32_bf16 v[56:59], v[90:93], v[114:117], v[56:59]
	v_mfma_f32_16x16x32_bf16 v[60:63], v[90:93], v[118:121], v[60:63]
	ds_read_b128 v[90:93], v113 offset:49152
	ds_read_b128 v[32:35], v112 offset:34816
	ds_read_b128 v[94:97], v113 offset:51200
	ds_read_b128 v[114:117], v113 offset:53248
	ds_read_b128 v[118:121], v113 offset:55296
	s_waitcnt lgkmcnt(0)
	v_mfma_f32_16x16x32_bf16 v[0:3], v[16:19], v[90:93], v[0:3]
	v_mfma_f32_16x16x32_bf16 v[4:7], v[16:19], v[94:97], v[4:7]
	v_mfma_f32_16x16x32_bf16 v[8:11], v[16:19], v[114:117], v[8:11]
	v_mfma_f32_16x16x32_bf16 v[16:19], v[16:19], v[118:121], v[12:15]
	v_mfma_f32_16x16x32_bf16 v[12:15], v[32:35], v[90:93], v[82:85]
	ds_read_b128 v[48:51], v112 offset:36864
	s_nop 1
	ds_read_b128 v[82:85], v112 offset:38912
	s_waitcnt vmcnt(0) lgkmcnt(0)
	s_barrier
	s_cbranch_vccnz .Lge1_exit1
	s_setprio 1
	v_mfma_f32_16x16x32_bf16 v[20:23], v[32:35], v[94:97], v[20:23]
	s_add_i32 m0, s69, 0x8000
	v_lshl_add_u64 v[246:247], s[4:5], 0, v[66:67]
	v_lshl_add_u64 v[246:247], v[246:247], 0, s[16:17]
	global_load_lds_dwordx4 v[246:247], off
	v_mfma_f32_16x16x32_bf16 v[24:27], v[32:35], v[114:117], v[24:27]
	s_add_i32 m0, s69, 0xc000
	v_lshl_add_u64 v[246:247], s[4:5], 0, v[74:75]
	v_lshl_add_u64 v[246:247], v[246:247], 0, s[18:19]
	global_load_lds_dwordx4 v[246:247], off
	v_mfma_f32_16x16x32_bf16 v[32:35], v[32:35], v[118:121], v[28:31]
	s_add_i32 m0, s69, 0x8400
	v_lshl_add_u64 v[246:247], s[4:5], 0, v[68:69]
	v_lshl_add_u64 v[246:247], v[246:247], 0, s[16:17]
	global_load_lds_dwordx4 v[246:247], off
	s_waitcnt lgkmcnt(0)
	v_mfma_f32_16x16x32_bf16 v[28:31], v[48:51], v[90:93], v[122:125]
	s_add_i32 m0, s69, 0xc400
	v_lshl_add_u64 v[246:247], s[4:5], 0, v[76:77]
	v_lshl_add_u64 v[246:247], v[246:247], 0, s[18:19]
	global_load_lds_dwordx4 v[246:247], off
	v_mfma_f32_16x16x32_bf16 v[36:39], v[48:51], v[94:97], v[36:39]
	s_add_i32 m0, s69, 0x8800
	v_lshl_add_u64 v[246:247], s[4:5], 0, v[70:71]
	v_lshl_add_u64 v[246:247], v[246:247], 0, s[16:17]
	global_load_lds_dwordx4 v[246:247], off
	v_mfma_f32_16x16x32_bf16 v[40:43], v[48:51], v[114:117], v[40:43]
	s_add_i32 m0, s69, 0xc800
	v_lshl_add_u64 v[246:247], s[4:5], 0, v[78:79]
	v_lshl_add_u64 v[246:247], v[246:247], 0, s[18:19]
	global_load_lds_dwordx4 v[246:247], off
	v_mfma_f32_16x16x32_bf16 v[48:51], v[48:51], v[118:121], v[44:47]
	s_add_i32 m0, s75, 0x8000
	v_lshl_add_u64 v[246:247], s[4:5], 0, v[72:73]
	v_lshl_add_u64 v[246:247], v[246:247], 0, s[16:17]
	global_load_lds_dwordx4 v[246:247], off
	v_mfma_f32_16x16x32_bf16 v[44:47], v[82:85], v[90:93], v[86:89]
	s_add_i32 m0, s75, 0xc000
	v_lshl_add_u64 v[246:247], s[4:5], 0, v[80:81]
	v_lshl_add_u64 v[246:247], v[246:247], 0, s[18:19]
	global_load_lds_dwordx4 v[246:247], off
	v_mfma_f32_16x16x32_bf16 v[52:55], v[82:85], v[94:97], v[52:55]
	v_mfma_f32_16x16x32_bf16 v[56:59], v[82:85], v[114:117], v[56:59]
	v_mfma_f32_16x16x32_bf16 v[60:63], v[82:85], v[118:121], v[60:63]
	s_cmpk_gt_u32 s9, 0x37f
	s_branch .Lge1_k0

; #define GBAR() do { asm volatile("s_waitcnt vmcnt(0) lgkmcnt(0)" ::: "memory"); __builtin_amdgcn_s_barrier(); } while (0)
; template <int EPI, bool GUARD>
; DEVI void gemm_tile(const Params& p, const bf16_t* __restrict__ A, int lda, const bf16_t* __restrict__ Bt, int ldb, int K,
;                           int row_base, int row_lo, int row_hi, int tile_n, int layer, int which, char* lds) {
;     ...
;   const int swz = c16 >> 1;
;   int koff[2];
; #pragma unroll
;   for (int ks = 0; ks < 2; ++ks) koff[ks] = ((ks * 4 + q4) ^ swz) << 4;
;   const int arow = (wr * 64 + c16) * 128, brow = 16384 + (wc * 64 + c16) * 128;
;     ...
;   GISSUE(0, 0); GBAR();
;   for (int k0 = 0; k0 < K; k0 += 128) {
;     GISSUE(k0 + 64, 1);
;     KSTEPS(0);
;     GBAR();
;     if (k0 + 128 < K) GISSUE(k0 + 128, 0);
;     KSTEPS(1);
;     GBAR();
;   }
.Lge1_k0:
	ds_read_b128 v[114:117], v64
	ds_read_b128 v[118:121], v111 offset:16384
	ds_read_b128 v[122:125], v64 offset:2048
	ds_read_b128 v[126:129], v111 offset:18432
	ds_read_b128 v[130:133], v111 offset:20480
	ds_read_b128 v[134:137], v111 offset:22528
	s_waitcnt lgkmcnt(0)
	v_mfma_f32_16x16x32_bf16 v[0:3], v[114:117], v[118:121], v[0:3]
	s_cselect_b64 s[6:7], -1, 0
	s_and_b64 vcc, exec, s[6:7]
	v_mfma_f32_16x16x32_bf16 v[4:7], v[114:117], v[126:129], v[4:7]
	v_mfma_f32_16x16x32_bf16 v[8:11], v[114:117], v[130:133], v[8:11]
	v_mfma_f32_16x16x32_bf16 v[16:19], v[114:117], v[134:137], v[16:19]
	v_mfma_f32_16x16x32_bf16 v[114:117], v[122:125], v[118:121], v[12:15]
	v_mfma_f32_16x16x32_bf16 v[20:23], v[122:125], v[126:129], v[20:23]
	v_mfma_f32_16x16x32_bf16 v[24:27], v[122:125], v[130:133], v[24:27]
	v_mfma_f32_16x16x32_bf16 v[32:35], v[122:125], v[134:137], v[32:35]
	s_setprio 0
	ds_read_b128 v[12:15], v64 offset:4096
	ds_read_b128 v[122:125], v64 offset:6144
	s_waitcnt lgkmcnt(0)
	v_mfma_f32_16x16x32_bf16 v[138:141], v[12:15], v[118:121], v[28:31]
	v_mfma_f32_16x16x32_bf16 v[36:39], v[12:15], v[126:129], v[36:39]
	v_mfma_f32_16x16x32_bf16 v[40:43], v[12:15], v[130:133], v[40:43]
	v_mfma_f32_16x16x32_bf16 v[48:51], v[12:15], v[134:137], v[48:51]
	ds_read_b128 v[12:15], v112
	v_mfma_f32_16x16x32_bf16 v[118:121], v[122:125], v[118:121], v[44:47]
	v_mfma_f32_16x16x32_bf16 v[52:55], v[122:125], v[126:129], v[52:55]
	v_mfma_f32_16x16x32_bf16 v[56:59], v[122:125], v[130:133], v[56:59]
	v_mfma_f32_16x16x32_bf16 v[60:63], v[122:125], v[134:137], v[60:63]
	ds_read_b128 v[122:125], v113 offset:16384
	ds_read_b128 v[28:31], v112 offset:2048
	ds_read_b128 v[126:129], v113 offset:18432
	ds_read_b128 v[130:133], v113 offset:20480
	ds_read_b128 v[134:137], v113 offset:22528
	s_waitcnt lgkmcnt(0)
	v_mfma_f32_16x16x32_bf16 v[0:3], v[12:15], v[122:125], v[0:3]
	v_mfma_f32_16x16x32_bf16 v[4:7], v[12:15], v[126:129], v[4:7]
	v_mfma_f32_16x16x32_bf16 v[8:11], v[12:15], v[130:133], v[8:11]
	v_mfma_f32_16x16x32_bf16 v[12:15], v[12:15], v[134:137], v[16:19]
	v_mfma_f32_16x16x32_bf16 v[16:19], v[28:31], v[122:125], v[114:117]
	ds_read_b128 v[44:47], v112 offset:4096
	s_nop 1
	ds_read_b128 v[114:117], v112 offset:6144
	s_waitcnt vmcnt(0) lgkmcnt(0)
	s_barrier
	s_cbranch_vccnz .Lge1_last0
	s_setprio 1
	v_mfma_f32_16x16x32_bf16 v[20:23], v[28:31], v[126:129], v[20:23]
	s_mov_b32 m0, s69
	v_lshl_add_u64 v[246:247], s[4:5], 0, v[66:67]
	v_lshl_add_u64 v[246:247], v[246:247], 0, s[26:27]
	global_load_lds_dwordx4 v[246:247], off
	v_mfma_f32_16x16x32_bf16 v[24:27], v[28:31], v[130:133], v[24:27]
	s_mov_b32 m0, s70
	v_lshl_add_u64 v[246:247], s[4:5], 0, v[74:75]
	v_lshl_add_u64 v[246:247], v[246:247], 0, s[34:35]
	global_load_lds_dwordx4 v[246:247], off
	v_mfma_f32_16x16x32_bf16 v[28:31], v[28:31], v[134:137], v[32:35]
	s_mov_b32 m0, s71
	v_lshl_add_u64 v[246:247], s[4:5], 0, v[68:69]
	v_lshl_add_u64 v[246:247], v[246:247], 0, s[26:27]
	global_load_lds_dwordx4 v[246:247], off
	s_waitcnt lgkmcnt(0)
	v_mfma_f32_16x16x32_bf16 v[32:35], v[44:47], v[122:125], v[138:141]
	s_mov_b32 m0, s72
	v_lshl_add_u64 v[246:247], s[4:5], 0, v[76:77]
	v_lshl_add_u64 v[246:247], v[246:247], 0, s[34:35]
	global_load_lds_dwordx4 v[246:247], off
	v_mfma_f32_16x16x32_bf16 v[36:39], v[44:47], v[126:129], v[36:39]
	s_mov_b32 m0, s73
	v_lshl_add_u64 v[246:247], s[4:5], 0, v[70:71]
	v_lshl_add_u64 v[246:247], v[246:247], 0, s[26:27]
	global_load_lds_dwordx4 v[246:247], off
	v_mfma_f32_16x16x32_bf16 v[40:43], v[44:47], v[130:133], v[40:43]
	s_mov_b32 m0, s74
	v_lshl_add_u64 v[246:247], s[4:5], 0, v[78:79]
	v_lshl_add_u64 v[246:247], v[246:247], 0, s[34:35]
	global_load_lds_dwordx4 v[246:247], off
	v_mfma_f32_16x16x32_bf16 v[44:47], v[44:47], v[134:137], v[48:51]
	s_mov_b32 m0, s75
	v_lshl_add_u64 v[246:247], s[4:5], 0, v[72:73]
	v_lshl_add_u64 v[246:247], v[246:247], 0, s[26:27]
	global_load_lds_dwordx4 v[246:247], off
	v_mfma_f32_16x16x32_bf16 v[48:51], v[114:117], v[122:125], v[118:121]
	s_mov_b32 m0, s76
	v_lshl_add_u64 v[246:247], s[4:5], 0, v[80:81]
	v_lshl_add_u64 v[246:247], v[246:247], 0, s[34:35]
	global_load_lds_dwordx4 v[246:247], off
	v_mfma_f32_16x16x32_bf16 v[52:55], v[114:117], v[126:129], v[52:55]
	v_mfma_f32_16x16x32_bf16 v[56:59], v[114:117], v[130:133], v[56:59]
	v_mfma_f32_16x16x32_bf16 v[60:63], v[114:117], v[134:137], v[60:63]
	s_branch .LBB0_667

; #define GBAR() do { asm volatile("s_waitcnt vmcnt(0) lgkmcnt(0)" ::: "memory"); __builtin_amdgcn_s_barrier(); } while (0)
; template <int EPI, bool GUARD>
; DEVI void gemm_tile(const Params& p, const bf16_t* __restrict__ A, int lda, const bf16_t* __restrict__ Bt, int ldb, int K,
;                           int row_base, int row_lo, int row_hi, int tile_n, int layer, int which, char* lds) {
;     ...
;   const int swz = c16 >> 1;
;   int koff[2];
; #pragma unroll
;   for (int ks = 0; ks < 2; ++ks) koff[ks] = ((ks * 4 + q4) ^ swz) << 4;
;   const int arow = (wr * 64 + c16) * 128, brow = 16384 + (wc * 64 + c16) * 128;
;     ...
;   GISSUE(0, 0); GBAR();
;   for (int k0 = 0; k0 < K; k0 += 128) {
;     GISSUE(k0 + 64, 1);
;     KSTEPS(0);
;     GBAR();
;     if (k0 + 128 < K) GISSUE(k0 + 128, 0);
;     KSTEPS(1);
;     GBAR();
;   }
.LBB0_745:
	ds_read_b128 v[82:85], v64 offset:32768
	ds_read_b128 v[86:89], v107 offset:49152
	ds_read_b128 v[90:93], v64 offset:34816
	ds_read_b128 v[94:97], v107 offset:51200
	ds_read_b128 v[110:113], v107 offset:53248
	ds_read_b128 v[114:117], v107 offset:55296
	s_addk_i32 s62, 0x80
	s_waitcnt lgkmcnt(0)
	v_mfma_f32_16x16x32_bf16 v[0:3], v[82:85], v[86:89], v[0:3]
	s_add_u32 s26, s26, 0x100
	s_addc_u32 s27, s27, 0
	s_andn2_b64 vcc, exec, s[34:35]
	v_mfma_f32_16x16x32_bf16 v[4:7], v[82:85], v[94:97], v[4:7]
	v_mfma_f32_16x16x32_bf16 v[8:11], v[82:85], v[110:113], v[8:11]
	v_mfma_f32_16x16x32_bf16 v[12:15], v[82:85], v[114:117], v[12:15]
	v_mfma_f32_16x16x32_bf16 v[16:19], v[90:93], v[86:89], v[16:19]
	v_mfma_f32_16x16x32_bf16 v[20:23], v[90:93], v[94:97], v[20:23]
	v_mfma_f32_16x16x32_bf16 v[24:27], v[90:93], v[110:113], v[24:27]
	v_mfma_f32_16x16x32_bf16 v[28:31], v[90:93], v[114:117], v[28:31]
	s_setprio 0
	ds_read_b128 v[82:85], v64 offset:36864
	ds_read_b128 v[90:93], v64 offset:38912
	s_waitcnt lgkmcnt(0)
	v_mfma_f32_16x16x32_bf16 v[118:121], v[82:85], v[86:89], v[32:35]
	s_nop 2
	ds_read_b128 v[32:35], v108 offset:32768
	v_mfma_f32_16x16x32_bf16 v[122:125], v[82:85], v[94:97], v[36:39]
	v_mfma_f32_16x16x32_bf16 v[126:129], v[82:85], v[110:113], v[40:43]
	v_mfma_f32_16x16x32_bf16 v[82:85], v[82:85], v[114:117], v[44:47]
	v_mfma_f32_16x16x32_bf16 v[86:89], v[90:93], v[86:89], v[48:51]
	v_mfma_f32_16x16x32_bf16 v[94:97], v[90:93], v[94:97], v[52:55]
	v_mfma_f32_16x16x32_bf16 v[110:113], v[90:93], v[110:113], v[56:59]
	v_mfma_f32_16x16x32_bf16 v[90:93], v[90:93], v[114:117], v[60:63]
	ds_read_b128 v[114:117], v109 offset:49152
	ds_read_b128 v[130:133], v108 offset:34816
	ds_read_b128 v[134:137], v109 offset:51200
	ds_read_b128 v[138:141], v109 offset:53248
	ds_read_b128 v[142:145], v109 offset:55296
	s_waitcnt lgkmcnt(0)
	v_mfma_f32_16x16x32_bf16 v[60:63], v[32:35], v[114:117], v[0:3]
	v_mfma_f32_16x16x32_bf16 v[52:55], v[32:35], v[138:141], v[8:11]
	s_nop 1
	ds_read_b128 v[0:3], v108 offset:36864
	ds_read_b128 v[8:11], v108 offset:38912
	s_waitcnt vmcnt(0) lgkmcnt(0)
	s_barrier
	s_cbranch_vccz .Lge2_exit1
	s_setprio 1
	v_mfma_f32_16x16x32_bf16 v[56:59], v[32:35], v[134:137], v[4:7]
	s_mov_b32 m0, s63
	v_lshl_add_u64 v[246:247], s[26:27], 0, v[66:67]
	v_lshl_add_u64 v[246:247], v[246:247], 0, s[4:5]
	global_load_lds_dwordx4 v[246:247], off
	v_mfma_f32_16x16x32_bf16 v[48:51], v[32:35], v[142:145], v[12:15]
	s_mov_b32 m0, s72
	v_lshl_add_u64 v[246:247], s[26:27], 0, v[74:75]
	v_lshl_add_u64 v[246:247], v[246:247], 0, s[6:7]
	global_load_lds_dwordx4 v[246:247], off
	v_mfma_f32_16x16x32_bf16 v[44:47], v[130:133], v[114:117], v[16:19]
	s_mov_b32 m0, s68
	v_lshl_add_u64 v[246:247], s[26:27], 0, v[68:69]
	v_lshl_add_u64 v[246:247], v[246:247], 0, s[4:5]
	global_load_lds_dwordx4 v[246:247], off
	v_mfma_f32_16x16x32_bf16 v[40:43], v[130:133], v[134:137], v[20:23]
	s_mov_b32 m0, s69
	v_lshl_add_u64 v[246:247], s[26:27], 0, v[76:77]
	v_lshl_add_u64 v[246:247], v[246:247], 0, s[6:7]
	global_load_lds_dwordx4 v[246:247], off
	v_mfma_f32_16x16x32_bf16 v[36:39], v[130:133], v[138:141], v[24:27]
	s_mov_b32 m0, s70
	v_lshl_add_u64 v[246:247], s[26:27], 0, v[70:71]
	v_lshl_add_u64 v[246:247], v[246:247], 0, s[4:5]
	global_load_lds_dwordx4 v[246:247], off
	v_mfma_f32_16x16x32_bf16 v[32:35], v[130:133], v[142:145], v[28:31]
	s_mov_b32 m0, s71
	v_lshl_add_u64 v[246:247], s[26:27], 0, v[78:79]
	v_lshl_add_u64 v[246:247], v[246:247], 0, s[6:7]
	global_load_lds_dwordx4 v[246:247], off
	s_waitcnt lgkmcnt(0)
	v_mfma_f32_16x16x32_bf16 v[28:31], v[0:3], v[114:117], v[118:121]
	s_mov_b32 m0, s73
	v_lshl_add_u64 v[246:247], s[26:27], 0, v[72:73]
	v_lshl_add_u64 v[246:247], v[246:247], 0, s[4:5]
	global_load_lds_dwordx4 v[246:247], off
	v_mfma_f32_16x16x32_bf16 v[24:27], v[0:3], v[134:137], v[122:125]
	s_mov_b32 m0, s74
	v_lshl_add_u64 v[246:247], s[26:27], 0, v[80:81]
	v_lshl_add_u64 v[246:247], v[246:247], 0, s[6:7]
	global_load_lds_dwordx4 v[246:247], off
	v_mfma_f32_16x16x32_bf16 v[16:19], v[0:3], v[138:141], v[126:129]
	v_mfma_f32_16x16x32_bf16 v[12:15], v[0:3], v[142:145], v[82:85]
	v_mfma_f32_16x16x32_bf16 v[4:7], v[8:11], v[114:117], v[86:89]
	v_mfma_f32_16x16x32_bf16 v[0:3], v[8:11], v[134:137], v[94:97]
	v_mfma_f32_16x16x32_bf16 v[20:23], v[8:11], v[138:141], v[110:113]
	v_mfma_f32_16x16x32_bf16 v[8:11], v[8:11], v[142:145], v[90:93]
	s_cmpk_gt_u32 s62, 0xa7f
	s_cselect_b64 s[34:35], -1, 0
	s_and_b64 vcc, exec, s[34:35]
	s_branch .Lge2_k0

; #define GBAR() do { asm volatile("s_waitcnt vmcnt(0) lgkmcnt(0)" ::: "memory"); __builtin_amdgcn_s_barrier(); } while (0)
; template <int EPI, bool GUARD>
; DEVI void gemm_tile(const Params& p, const bf16_t* __restrict__ A, int lda, const bf16_t* __restrict__ Bt, int ldb, int K,
;                           int row_base, int row_lo, int row_hi, int tile_n, int layer, int which, char* lds) {
;     ...
;   const int swz = c16 >> 1;
;   int koff[2];
; #pragma unroll
;   for (int ks = 0; ks < 2; ++ks) koff[ks] = ((ks * 4 + q4) ^ swz) << 4;
;   const int arow = (wr * 64 + c16) * 128, brow = 16384 + (wc * 64 + c16) * 128;
;     ...
;   GISSUE(0, 0); GBAR();
;   for (int k0 = 0; k0 < K; k0 += 128) {
;     GISSUE(k0 + 64, 1);
;     KSTEPS(0);
;     GBAR();
;     if (k0 + 128 < K) GISSUE(k0 + 128, 0);
;     KSTEPS(1);
;     GBAR();
;   }
.Lge2_k0:
	ds_read_b128 v[110:113], v64
	ds_read_b128 v[114:117], v107 offset:16384
	ds_read_b128 v[118:121], v64 offset:2048
	ds_read_b128 v[122:125], v107 offset:18432
	ds_read_b128 v[126:129], v107 offset:20480
	ds_read_b128 v[130:133], v107 offset:22528
	s_waitcnt lgkmcnt(0)
	v_mfma_f32_16x16x32_bf16 v[60:63], v[110:113], v[114:117], v[60:63]
	v_mfma_f32_16x16x32_bf16 v[56:59], v[110:113], v[122:125], v[56:59]
	v_mfma_f32_16x16x32_bf16 v[52:55], v[110:113], v[126:129], v[52:55]
	v_mfma_f32_16x16x32_bf16 v[48:51], v[110:113], v[130:133], v[48:51]
	v_mfma_f32_16x16x32_bf16 v[44:47], v[118:121], v[114:117], v[44:47]
	v_mfma_f32_16x16x32_bf16 v[40:43], v[118:121], v[122:125], v[40:43]
	v_mfma_f32_16x16x32_bf16 v[36:39], v[118:121], v[126:129], v[36:39]
	v_mfma_f32_16x16x32_bf16 v[32:35], v[118:121], v[130:133], v[32:35]
	s_setprio 0
	ds_read_b128 v[110:113], v64 offset:4096
	ds_read_b128 v[118:121], v64 offset:6144
	s_waitcnt lgkmcnt(0)
	v_mfma_f32_16x16x32_bf16 v[134:137], v[110:113], v[114:117], v[28:31]
	v_mfma_f32_16x16x32_bf16 v[138:141], v[110:113], v[122:125], v[24:27]
	v_mfma_f32_16x16x32_bf16 v[142:145], v[110:113], v[126:129], v[16:19]
	v_mfma_f32_16x16x32_bf16 v[110:113], v[110:113], v[130:133], v[12:15]
	s_nop 2
	ds_read_b128 v[12:15], v108
	v_mfma_f32_16x16x32_bf16 v[114:117], v[118:121], v[114:117], v[4:7]
	v_mfma_f32_16x16x32_bf16 v[122:125], v[118:121], v[122:125], v[0:3]
	v_mfma_f32_16x16x32_bf16 v[126:129], v[118:121], v[126:129], v[20:23]
	v_mfma_f32_16x16x32_bf16 v[118:121], v[118:121], v[130:133], v[8:11]
	ds_read_b128 v[130:133], v109 offset:16384
	ds_read_b128 v[28:31], v108 offset:2048
	ds_read_b128 v[146:149], v109 offset:18432
	s_waitcnt lgkmcnt(0)
	v_mfma_f32_16x16x32_bf16 v[0:3], v[12:15], v[130:133], v[60:63]
	v_mfma_f32_16x16x32_bf16 v[4:7], v[12:15], v[146:149], v[56:59]
	s_nop 2
	ds_read_b128 v[56:59], v109 offset:20480
	ds_read_b128 v[60:63], v109 offset:22528
	v_mfma_f32_16x16x32_bf16 v[16:19], v[28:31], v[130:133], v[44:47]
	s_nop 2
	ds_read_b128 v[44:47], v108 offset:4096
	ds_read_b128 v[150:153], v108 offset:6144
	s_waitcnt vmcnt(0) lgkmcnt(0)
	s_barrier
	s_cbranch_vccnz .Lge2_last0
	s_setprio 1
	s_waitcnt lgkmcnt(0)
	v_mfma_f32_16x16x32_bf16 v[8:11], v[12:15], v[56:59], v[52:55]
	s_mov_b32 m0, s54
	v_lshl_add_u64 v[246:247], s[26:27], 0, v[66:67]
	v_lshl_add_u64 v[246:247], v[246:247], 0, s[8:9]
	global_load_lds_dwordx4 v[246:247], off
	v_mfma_f32_16x16x32_bf16 v[12:15], v[12:15], v[60:63], v[48:51]
	s_mov_b32 m0, s55
	v_lshl_add_u64 v[246:247], s[26:27], 0, v[74:75]
	v_lshl_add_u64 v[246:247], v[246:247], 0, s[16:17]
	global_load_lds_dwordx4 v[246:247], off
	v_mfma_f32_16x16x32_bf16 v[20:23], v[28:31], v[146:149], v[40:43]
	s_mov_b32 m0, s56
	v_lshl_add_u64 v[246:247], s[26:27], 0, v[68:69]
	v_lshl_add_u64 v[246:247], v[246:247], 0, s[8:9]
	global_load_lds_dwordx4 v[246:247], off
	v_mfma_f32_16x16x32_bf16 v[24:27], v[28:31], v[56:59], v[36:39]
	s_mov_b32 m0, s57
	v_lshl_add_u64 v[246:247], s[26:27], 0, v[76:77]
	v_lshl_add_u64 v[246:247], v[246:247], 0, s[16:17]
	global_load_lds_dwordx4 v[246:247], off
	v_mfma_f32_16x16x32_bf16 v[28:31], v[28:31], v[60:63], v[32:35]
	s_mov_b32 m0, s58
	v_lshl_add_u64 v[246:247], s[26:27], 0, v[70:71]
	v_lshl_add_u64 v[246:247], v[246:247], 0, s[8:9]
	global_load_lds_dwordx4 v[246:247], off
	v_mfma_f32_16x16x32_bf16 v[32:35], v[44:47], v[130:133], v[134:137]
	s_mov_b32 m0, s59
	v_lshl_add_u64 v[246:247], s[26:27], 0, v[78:79]
	v_lshl_add_u64 v[246:247], v[246:247], 0, s[16:17]
	global_load_lds_dwordx4 v[246:247], off
	v_mfma_f32_16x16x32_bf16 v[36:39], v[44:47], v[146:149], v[138:141]
	s_mov_b32 m0, s60
	v_lshl_add_u64 v[246:247], s[26:27], 0, v[72:73]
	v_lshl_add_u64 v[246:247], v[246:247], 0, s[8:9]
	global_load_lds_dwordx4 v[246:247], off
	v_mfma_f32_16x16x32_bf16 v[40:43], v[44:47], v[56:59], v[142:145]
	s_mov_b32 m0, s61
	v_lshl_add_u64 v[246:247], s[26:27], 0, v[80:81]
	v_lshl_add_u64 v[246:247], v[246:247], 0, s[16:17]
	global_load_lds_dwordx4 v[246:247], off
	v_mfma_f32_16x16x32_bf16 v[44:47], v[44:47], v[60:63], v[110:113]
	v_mfma_f32_16x16x32_bf16 v[48:51], v[150:153], v[130:133], v[114:117]
	v_mfma_f32_16x16x32_bf16 v[52:55], v[150:153], v[146:149], v[122:125]
	v_mfma_f32_16x16x32_bf16 v[56:59], v[150:153], v[56:59], v[126:129]
	v_mfma_f32_16x16x32_bf16 v[60:63], v[150:153], v[60:63], v[118:121]
	s_branch .LBB0_745

; #define GBAR() do { asm volatile("s_waitcnt vmcnt(0) lgkmcnt(0)" ::: "memory"); __builtin_amdgcn_s_barrier(); } while (0)
; template <int EPI, bool GUARD>
; DEVI void gemm_tile(const Params& p, const bf16_t* __restrict__ A, int lda, const bf16_t* __restrict__ Bt, int ldb, int K,
;                           int row_base, int row_lo, int row_hi, int tile_n, int layer, int which, char* lds) {
;     ...
;   const int swz = c16 >> 1;
;   int koff[2];
; #pragma unroll
;   for (int ks = 0; ks < 2; ++ks) koff[ks] = ((ks * 4 + q4) ^ swz) << 4;
;   const int arow = (wr * 64 + c16) * 128, brow = 16384 + (wc * 64 + c16) * 128;
;     ...
;   GISSUE(0, 0); GBAR();
;   for (int k0 = 0; k0 < K; k0 += 128) {
;     GISSUE(k0 + 64, 1);
;     KSTEPS(0);
;     GBAR();
;     if (k0 + 128 < K) GISSUE(k0 + 128, 0);
;     KSTEPS(1);
;     GBAR();
;   }
.LBB0_878:
	ds_read_b128 v[80:83], v101 offset:32768
	ds_read_b128 v[84:87], v102 offset:49152
	ds_read_b128 v[88:91], v101 offset:34816
	ds_read_b128 v[92:95], v102 offset:51200
	ds_read_b128 v[106:109], v102 offset:53248
	ds_read_b128 v[110:113], v102 offset:55296
	s_addk_i32 s85, 0x80
	s_waitcnt lgkmcnt(0)
	v_mfma_f32_16x16x32_bf16 v[0:3], v[80:83], v[84:87], v[0:3]
	s_add_u32 s4, s4, 0x100
	s_addc_u32 s5, s5, 0
	s_and_b64 vcc, exec, s[52:53]
	v_mfma_f32_16x16x32_bf16 v[4:7], v[80:83], v[92:95], v[4:7]
	v_mfma_f32_16x16x32_bf16 v[8:11], v[80:83], v[106:109], v[8:11]
	v_mfma_f32_16x16x32_bf16 v[12:15], v[80:83], v[110:113], v[12:15]
	v_mfma_f32_16x16x32_bf16 v[80:83], v[88:91], v[84:87], v[16:19]
	v_mfma_f32_16x16x32_bf16 v[20:23], v[88:91], v[92:95], v[20:23]
	v_mfma_f32_16x16x32_bf16 v[24:27], v[88:91], v[106:109], v[24:27]
	v_mfma_f32_16x16x32_bf16 v[28:31], v[88:91], v[110:113], v[28:31]
	s_setprio 0
	ds_read_b128 v[16:19], v101 offset:36864
	ds_read_b128 v[88:91], v101 offset:38912
	s_waitcnt lgkmcnt(0)
	v_mfma_f32_16x16x32_bf16 v[114:117], v[16:19], v[84:87], v[32:35]
	v_mfma_f32_16x16x32_bf16 v[36:39], v[16:19], v[92:95], v[36:39]
	v_mfma_f32_16x16x32_bf16 v[40:43], v[16:19], v[106:109], v[40:43]
	v_mfma_f32_16x16x32_bf16 v[44:47], v[16:19], v[110:113], v[44:47]
	ds_read_b128 v[16:19], v103 offset:32768
	v_mfma_f32_16x16x32_bf16 v[84:87], v[88:91], v[84:87], v[48:51]
	v_mfma_f32_16x16x32_bf16 v[52:55], v[88:91], v[92:95], v[52:55]
	v_mfma_f32_16x16x32_bf16 v[56:59], v[88:91], v[106:109], v[56:59]
	v_mfma_f32_16x16x32_bf16 v[60:63], v[88:91], v[110:113], v[60:63]
	ds_read_b128 v[88:91], v104 offset:49152
	ds_read_b128 v[32:35], v103 offset:34816
	ds_read_b128 v[92:95], v104 offset:51200
	ds_read_b128 v[106:109], v104 offset:53248
	ds_read_b128 v[110:113], v104 offset:55296
	s_waitcnt lgkmcnt(0)
	v_mfma_f32_16x16x32_bf16 v[0:3], v[16:19], v[88:91], v[0:3]
	v_mfma_f32_16x16x32_bf16 v[4:7], v[16:19], v[92:95], v[4:7]
	v_mfma_f32_16x16x32_bf16 v[8:11], v[16:19], v[106:109], v[8:11]
	v_mfma_f32_16x16x32_bf16 v[16:19], v[16:19], v[110:113], v[12:15]
	v_mfma_f32_16x16x32_bf16 v[12:15], v[32:35], v[88:91], v[80:83]
	ds_read_b128 v[48:51], v103 offset:36864
	s_nop 1
	ds_read_b128 v[80:83], v103 offset:38912
	s_waitcnt vmcnt(0) lgkmcnt(0)
	s_barrier
	s_cbranch_vccnz .Lge3_exit1
	s_setprio 1
	v_mfma_f32_16x16x32_bf16 v[20:23], v[32:35], v[92:95], v[20:23]
	s_add_i32 m0, s72, 0x8000
	v_lshl_add_u64 v[246:247], s[4:5], 0, v[64:65]
	v_lshl_add_u64 v[246:247], v[246:247], 0, s[16:17]
	global_load_lds_dwordx4 v[246:247], off
	v_mfma_f32_16x16x32_bf16 v[24:27], v[32:35], v[106:109], v[24:27]
	s_add_i32 m0, s72, 0xc000
	v_lshl_add_u64 v[246:247], s[4:5], 0, v[72:73]
	v_lshl_add_u64 v[246:247], v[246:247], 0, s[18:19]
	global_load_lds_dwordx4 v[246:247], off
	v_mfma_f32_16x16x32_bf16 v[32:35], v[32:35], v[110:113], v[28:31]
	s_add_i32 m0, s72, 0x8400
	v_lshl_add_u64 v[246:247], s[4:5], 0, v[66:67]
	v_lshl_add_u64 v[246:247], v[246:247], 0, s[16:17]
	global_load_lds_dwordx4 v[246:247], off
	s_waitcnt lgkmcnt(0)
	v_mfma_f32_16x16x32_bf16 v[28:31], v[48:51], v[88:91], v[114:117]
	s_add_i32 m0, s72, 0xc400
	v_lshl_add_u64 v[246:247], s[4:5], 0, v[74:75]
	v_lshl_add_u64 v[246:247], v[246:247], 0, s[18:19]
	global_load_lds_dwordx4 v[246:247], off
	v_mfma_f32_16x16x32_bf16 v[36:39], v[48:51], v[92:95], v[36:39]
	s_add_i32 m0, s72, 0x8800
	v_lshl_add_u64 v[246:247], s[4:5], 0, v[68:69]
	v_lshl_add_u64 v[246:247], v[246:247], 0, s[16:17]
	global_load_lds_dwordx4 v[246:247], off
	v_mfma_f32_16x16x32_bf16 v[40:43], v[48:51], v[106:109], v[40:43]
	s_add_i32 m0, s72, 0xc800
	v_lshl_add_u64 v[246:247], s[4:5], 0, v[76:77]
	v_lshl_add_u64 v[246:247], v[246:247], 0, s[18:19]
	global_load_lds_dwordx4 v[246:247], off
	v_mfma_f32_16x16x32_bf16 v[48:51], v[48:51], v[110:113], v[44:47]
	s_add_i32 m0, s78, 0x8000
	v_lshl_add_u64 v[246:247], s[4:5], 0, v[70:71]
	v_lshl_add_u64 v[246:247], v[246:247], 0, s[16:17]
	global_load_lds_dwordx4 v[246:247], off
	v_mfma_f32_16x16x32_bf16 v[44:47], v[80:83], v[88:91], v[84:87]
	s_add_i32 m0, s78, 0xc000
	v_lshl_add_u64 v[246:247], s[4:5], 0, v[78:79]
	v_lshl_add_u64 v[246:247], v[246:247], 0, s[18:19]
	global_load_lds_dwordx4 v[246:247], off
	v_mfma_f32_16x16x32_bf16 v[52:55], v[80:83], v[92:95], v[52:55]
	v_mfma_f32_16x16x32_bf16 v[56:59], v[80:83], v[106:109], v[56:59]
	v_mfma_f32_16x16x32_bf16 v[60:63], v[80:83], v[110:113], v[60:63]
	s_cmpk_gt_u32 s85, 0x37f
	s_branch .Lge3_k0

; #define GBAR() do { asm volatile("s_waitcnt vmcnt(0) lgkmcnt(0)" ::: "memory"); __builtin_amdgcn_s_barrier(); } while (0)
; template <int EPI, bool GUARD>
; DEVI void gemm_tile(const Params& p, const bf16_t* __restrict__ A, int lda, const bf16_t* __restrict__ Bt, int ldb, int K,
;                           int row_base, int row_lo, int row_hi, int tile_n, int layer, int which, char* lds) {
;     ...
;   const int swz = c16 >> 1;
;   int koff[2];
; #pragma unroll
;   for (int ks = 0; ks < 2; ++ks) koff[ks] = ((ks * 4 + q4) ^ swz) << 4;
;   const int arow = (wr * 64 + c16) * 128, brow = 16384 + (wc * 64 + c16) * 128;
;     ...
;   GISSUE(0, 0); GBAR();
;   for (int k0 = 0; k0 < K; k0 += 128) {
;     GISSUE(k0 + 64, 1);
;     KSTEPS(0);
;     GBAR();
;     if (k0 + 128 < K) GISSUE(k0 + 128, 0);
;     KSTEPS(1);
;     GBAR();
;   }
.Lge3_k0:
	ds_read_b128 v[106:109], v101
	ds_read_b128 v[110:113], v102 offset:16384
	ds_read_b128 v[114:117], v101 offset:2048
	ds_read_b128 v[118:121], v102 offset:18432
	ds_read_b128 v[122:125], v102 offset:20480
	ds_read_b128 v[130:133], v102 offset:22528
	s_waitcnt lgkmcnt(0)
	v_mfma_f32_16x16x32_bf16 v[0:3], v[106:109], v[110:113], v[0:3]
	s_cselect_b64 s[52:53], -1, 0
	s_and_b64 vcc, exec, s[52:53]
	v_mfma_f32_16x16x32_bf16 v[4:7], v[106:109], v[118:121], v[4:7]
	v_mfma_f32_16x16x32_bf16 v[8:11], v[106:109], v[122:125], v[8:11]
	v_mfma_f32_16x16x32_bf16 v[16:19], v[106:109], v[130:133], v[16:19]
	v_mfma_f32_16x16x32_bf16 v[106:109], v[114:117], v[110:113], v[12:15]
	v_mfma_f32_16x16x32_bf16 v[20:23], v[114:117], v[118:121], v[20:23]
	v_mfma_f32_16x16x32_bf16 v[24:27], v[114:117], v[122:125], v[24:27]
	v_mfma_f32_16x16x32_bf16 v[32:35], v[114:117], v[130:133], v[32:35]
	s_setprio 0
	ds_read_b128 v[12:15], v101 offset:4096
	ds_read_b128 v[114:117], v101 offset:6144
	s_waitcnt lgkmcnt(0)
	v_mfma_f32_16x16x32_bf16 v[140:143], v[12:15], v[110:113], v[28:31]
	v_mfma_f32_16x16x32_bf16 v[36:39], v[12:15], v[118:121], v[36:39]
	v_mfma_f32_16x16x32_bf16 v[40:43], v[12:15], v[122:125], v[40:43]
	v_mfma_f32_16x16x32_bf16 v[48:51], v[12:15], v[130:133], v[48:51]
	ds_read_b128 v[12:15], v103
	v_mfma_f32_16x16x32_bf16 v[110:113], v[114:117], v[110:113], v[44:47]
	v_mfma_f32_16x16x32_bf16 v[52:55], v[114:117], v[118:121], v[52:55]
	v_mfma_f32_16x16x32_bf16 v[56:59], v[114:117], v[122:125], v[56:59]
	v_mfma_f32_16x16x32_bf16 v[60:63], v[114:117], v[130:133], v[60:63]
	ds_read_b128 v[114:117], v104 offset:16384
	ds_read_b128 v[28:31], v103 offset:2048
	ds_read_b128 v[118:121], v104 offset:18432
	ds_read_b128 v[122:125], v104 offset:20480
	ds_read_b128 v[130:133], v104 offset:22528
	s_waitcnt lgkmcnt(0)
	v_mfma_f32_16x16x32_bf16 v[0:3], v[12:15], v[114:117], v[0:3]
	v_mfma_f32_16x16x32_bf16 v[4:7], v[12:15], v[118:121], v[4:7]
	v_mfma_f32_16x16x32_bf16 v[8:11], v[12:15], v[122:125], v[8:11]
	v_mfma_f32_16x16x32_bf16 v[12:15], v[12:15], v[130:133], v[16:19]
	v_mfma_f32_16x16x32_bf16 v[16:19], v[28:31], v[114:117], v[106:109]
	ds_read_b128 v[44:47], v103 offset:4096
	s_nop 1
	ds_read_b128 v[106:109], v103 offset:6144
	s_waitcnt vmcnt(0) lgkmcnt(0)
	s_barrier
	s_cbranch_vccnz .Lge3_last0
	s_setprio 1
	v_mfma_f32_16x16x32_bf16 v[20:23], v[28:31], v[118:121], v[20:23]
	s_mov_b32 m0, s72
	v_lshl_add_u64 v[246:247], s[4:5], 0, v[64:65]
	v_lshl_add_u64 v[246:247], v[246:247], 0, s[26:27]
	global_load_lds_dwordx4 v[246:247], off
	v_mfma_f32_16x16x32_bf16 v[24:27], v[28:31], v[122:125], v[24:27]
	s_mov_b32 m0, s73
	v_lshl_add_u64 v[246:247], s[4:5], 0, v[72:73]
	v_lshl_add_u64 v[246:247], v[246:247], 0, s[34:35]
	global_load_lds_dwordx4 v[246:247], off
	v_mfma_f32_16x16x32_bf16 v[28:31], v[28:31], v[130:133], v[32:35]
	s_mov_b32 m0, s74
	v_lshl_add_u64 v[246:247], s[4:5], 0, v[66:67]
	v_lshl_add_u64 v[246:247], v[246:247], 0, s[26:27]
	global_load_lds_dwordx4 v[246:247], off
	s_waitcnt lgkmcnt(0)
	v_mfma_f32_16x16x32_bf16 v[32:35], v[44:47], v[114:117], v[140:143]
	s_mov_b32 m0, s75
	v_lshl_add_u64 v[246:247], s[4:5], 0, v[74:75]
	v_lshl_add_u64 v[246:247], v[246:247], 0, s[34:35]
	global_load_lds_dwordx4 v[246:247], off
	v_mfma_f32_16x16x32_bf16 v[36:39], v[44:47], v[118:121], v[36:39]
	s_mov_b32 m0, s76
	v_lshl_add_u64 v[246:247], s[4:5], 0, v[68:69]
	v_lshl_add_u64 v[246:247], v[246:247], 0, s[26:27]
	global_load_lds_dwordx4 v[246:247], off
	v_mfma_f32_16x16x32_bf16 v[40:43], v[44:47], v[122:125], v[40:43]
	s_mov_b32 m0, s77
	v_lshl_add_u64 v[246:247], s[4:5], 0, v[76:77]
	v_lshl_add_u64 v[246:247], v[246:247], 0, s[34:35]
	global_load_lds_dwordx4 v[246:247], off
	v_mfma_f32_16x16x32_bf16 v[44:47], v[44:47], v[130:133], v[48:51]
	s_mov_b32 m0, s78
	v_lshl_add_u64 v[246:247], s[4:5], 0, v[70:71]
	v_lshl_add_u64 v[246:247], v[246:247], 0, s[26:27]
	global_load_lds_dwordx4 v[246:247], off
	v_mfma_f32_16x16x32_bf16 v[48:51], v[106:109], v[114:117], v[110:113]
	s_mov_b32 m0, s79
	v_lshl_add_u64 v[246:247], s[4:5], 0, v[78:79]
	v_lshl_add_u64 v[246:247], v[246:247], 0, s[34:35]
	global_load_lds_dwordx4 v[246:247], off
	v_mfma_f32_16x16x32_bf16 v[52:55], v[106:109], v[118:121], v[52:55]
	v_mfma_f32_16x16x32_bf16 v[56:59], v[106:109], v[122:125], v[56:59]
	v_mfma_f32_16x16x32_bf16 v[60:63], v[106:109], v[130:133], v[60:63]
	s_branch .LBB0_878

; #define GBAR() do { asm volatile("s_waitcnt vmcnt(0) lgkmcnt(0)" ::: "memory"); __builtin_amdgcn_s_barrier(); } while (0)
; template <int EPI, bool GUARD>
; DEVI void gemm_tile(const Params& p, const bf16_t* __restrict__ A, int lda, const bf16_t* __restrict__ Bt, int ldb, int K,
;                           int row_base, int row_lo, int row_hi, int tile_n, int layer, int which, char* lds) {
;     ...
;   const int swz = c16 >> 1;
;   int koff[2];
; #pragma unroll
;   for (int ks = 0; ks < 2; ++ks) koff[ks] = ((ks * 4 + q4) ^ swz) << 4;
;   const int arow = (wr * 64 + c16) * 128, brow = 16384 + (wc * 64 + c16) * 128;
;     ...
;   GISSUE(0, 0); GBAR();
;   for (int k0 = 0; k0 < K; k0 += 128) {
;     GISSUE(k0 + 64, 1);
;     KSTEPS(0);
;     GBAR();
;     if (k0 + 128 < K) GISSUE(k0 + 128, 0);
;     KSTEPS(1);
;     GBAR();
;   }
.LBB0_959:
	ds_read_b128 v[82:85], v64 offset:32768
	ds_read_b128 v[86:89], v103 offset:49152
	ds_read_b128 v[90:93], v64 offset:34816
	ds_read_b128 v[94:97], v103 offset:51200
	ds_read_b128 v[106:109], v103 offset:53248
	ds_read_b128 v[110:113], v103 offset:55296
	s_addk_i32 s69, 0x80
	s_waitcnt lgkmcnt(0)
	v_mfma_f32_16x16x32_bf16 v[0:3], v[82:85], v[86:89], v[0:3]
	s_add_u32 s34, s34, 0x100
	s_addc_u32 s35, s35, 0
	s_and_b64 vcc, exec, s[44:45]
	v_mfma_f32_16x16x32_bf16 v[4:7], v[82:85], v[94:97], v[4:7]
	v_mfma_f32_16x16x32_bf16 v[8:11], v[82:85], v[106:109], v[8:11]
	v_mfma_f32_16x16x32_bf16 v[82:85], v[82:85], v[110:113], v[12:15]
	v_mfma_f32_16x16x32_bf16 v[16:19], v[90:93], v[86:89], v[16:19]
	v_mfma_f32_16x16x32_bf16 v[20:23], v[90:93], v[94:97], v[20:23]
	v_mfma_f32_16x16x32_bf16 v[24:27], v[90:93], v[106:109], v[24:27]
	v_mfma_f32_16x16x32_bf16 v[28:31], v[90:93], v[110:113], v[28:31]
	s_setprio 0
	ds_read_b128 v[12:15], v64 offset:36864
	ds_read_b128 v[90:93], v64 offset:38912
	s_waitcnt lgkmcnt(0)
	v_mfma_f32_16x16x32_bf16 v[114:117], v[12:15], v[94:97], v[36:39]
	v_mfma_f32_16x16x32_bf16 v[52:55], v[90:93], v[94:97], v[52:55]
	ds_read_b128 v[94:97], v104 offset:32768
	v_mfma_f32_16x16x32_bf16 v[32:35], v[12:15], v[86:89], v[32:35]
	v_mfma_f32_16x16x32_bf16 v[40:43], v[12:15], v[106:109], v[40:43]
	v_mfma_f32_16x16x32_bf16 v[44:47], v[12:15], v[110:113], v[44:47]
	v_mfma_f32_16x16x32_bf16 v[86:89], v[90:93], v[86:89], v[48:51]
	v_mfma_f32_16x16x32_bf16 v[56:59], v[90:93], v[106:109], v[56:59]
	v_mfma_f32_16x16x32_bf16 v[60:63], v[90:93], v[110:113], v[60:63]
	ds_read_b128 v[90:93], v105 offset:49152
	ds_read_b128 v[106:109], v104 offset:34816
	ds_read_b128 v[110:113], v105 offset:51200
	ds_read_b128 v[118:121], v105 offset:53248
	ds_read_b128 v[128:131], v105 offset:55296
	s_waitcnt lgkmcnt(0)
	v_mfma_f32_16x16x32_bf16 v[48:51], v[94:97], v[90:93], v[0:3]
	v_mfma_f32_16x16x32_bf16 v[36:39], v[94:97], v[110:113], v[4:7]
	v_mfma_f32_16x16x32_bf16 v[12:15], v[94:97], v[118:121], v[8:11]
	v_mfma_f32_16x16x32_bf16 v[8:11], v[94:97], v[128:131], v[82:85]
	s_nop 2
	ds_read_b128 v[82:85], v104 offset:36864
	ds_read_b128 v[94:97], v104 offset:38912
	s_waitcnt vmcnt(0) lgkmcnt(0)
	s_barrier
	s_cbranch_vccnz .Lge4_exit1
	s_setprio 1
	v_mfma_f32_16x16x32_bf16 v[4:7], v[106:109], v[90:93], v[16:19]
	s_add_i32 m0, s59, 0x8000
	v_lshl_add_u64 v[246:247], s[34:35], 0, v[66:67]
	v_lshl_add_u64 v[246:247], v[246:247], 0, s[4:5]
	global_load_lds_dwordx4 v[246:247], off
	v_mfma_f32_16x16x32_bf16 v[0:3], v[106:109], v[110:113], v[20:23]
	s_add_i32 m0, s59, 0xc000
	v_lshl_add_u64 v[246:247], s[34:35], 0, v[74:75]
	v_lshl_add_u64 v[246:247], v[246:247], 0, s[16:17]
	global_load_lds_dwordx4 v[246:247], off
	v_mfma_f32_16x16x32_bf16 v[16:19], v[106:109], v[118:121], v[24:27]
	s_add_i32 m0, s59, 0x8400
	v_lshl_add_u64 v[246:247], s[34:35], 0, v[68:69]
	v_lshl_add_u64 v[246:247], v[246:247], 0, s[4:5]
	global_load_lds_dwordx4 v[246:247], off
	v_mfma_f32_16x16x32_bf16 v[24:27], v[106:109], v[128:131], v[28:31]
	s_add_i32 m0, s59, 0xc400
	v_lshl_add_u64 v[246:247], s[34:35], 0, v[76:77]
	v_lshl_add_u64 v[246:247], v[246:247], 0, s[16:17]
	global_load_lds_dwordx4 v[246:247], off
	s_waitcnt lgkmcnt(0)
	v_mfma_f32_16x16x32_bf16 v[20:23], v[82:85], v[90:93], v[32:35]
	s_add_i32 m0, s59, 0x8800
	v_lshl_add_u64 v[246:247], s[34:35], 0, v[70:71]
	v_lshl_add_u64 v[246:247], v[246:247], 0, s[4:5]
	global_load_lds_dwordx4 v[246:247], off
	v_mfma_f32_16x16x32_bf16 v[28:31], v[82:85], v[110:113], v[114:117]
	s_add_i32 m0, s59, 0xc800
	v_lshl_add_u64 v[246:247], s[34:35], 0, v[78:79]
	v_lshl_add_u64 v[246:247], v[246:247], 0, s[16:17]
	global_load_lds_dwordx4 v[246:247], off
	v_mfma_f32_16x16x32_bf16 v[32:35], v[82:85], v[118:121], v[40:43]
	s_add_i32 m0, s65, 0x8000
	v_lshl_add_u64 v[246:247], s[34:35], 0, v[72:73]
	v_lshl_add_u64 v[246:247], v[246:247], 0, s[4:5]
	global_load_lds_dwordx4 v[246:247], off
	v_mfma_f32_16x16x32_bf16 v[44:47], v[82:85], v[128:131], v[44:47]
	s_add_i32 m0, s65, 0xc000
	v_lshl_add_u64 v[246:247], s[34:35], 0, v[80:81]
	v_lshl_add_u64 v[246:247], v[246:247], 0, s[16:17]
	global_load_lds_dwordx4 v[246:247], off
	v_mfma_f32_16x16x32_bf16 v[40:43], v[94:97], v[90:93], v[86:89]
	v_mfma_f32_16x16x32_bf16 v[52:55], v[94:97], v[110:113], v[52:55]
	v_mfma_f32_16x16x32_bf16 v[56:59], v[94:97], v[118:121], v[56:59]
	v_mfma_f32_16x16x32_bf16 v[60:63], v[94:97], v[128:131], v[60:63]
	s_cmpk_gt_u32 s69, 0x27f
	s_branch .Lge4_k0

; #define GBAR() do { asm volatile("s_waitcnt vmcnt(0) lgkmcnt(0)" ::: "memory"); __builtin_amdgcn_s_barrier(); } while (0)
; template <int EPI, bool GUARD>
; DEVI void gemm_tile(const Params& p, const bf16_t* __restrict__ A, int lda, const bf16_t* __restrict__ Bt, int ldb, int K,
;                           int row_base, int row_lo, int row_hi, int tile_n, int layer, int which, char* lds) {
;     ...
;   const int swz = c16 >> 1;
;   int koff[2];
; #pragma unroll
;   for (int ks = 0; ks < 2; ++ks) koff[ks] = ((ks * 4 + q4) ^ swz) << 4;
;   const int arow = (wr * 64 + c16) * 128, brow = 16384 + (wc * 64 + c16) * 128;
;     ...
;   GISSUE(0, 0); GBAR();
;   for (int k0 = 0; k0 < K; k0 += 128) {
;     GISSUE(k0 + 64, 1);
;     KSTEPS(0);
;     GBAR();
;     if (k0 + 128 < K) GISSUE(k0 + 128, 0);
;     KSTEPS(1);
;     GBAR();
;   }
.Lge4_k0:
	ds_read_b128 v[106:109], v64
	ds_read_b128 v[110:113], v103 offset:16384
	ds_read_b128 v[114:117], v64 offset:2048
	ds_read_b128 v[118:121], v103 offset:18432
	ds_read_b128 v[128:131], v103 offset:20480
	ds_read_b128 v[136:139], v103 offset:22528
	s_waitcnt lgkmcnt(0)
	v_mfma_f32_16x16x32_bf16 v[140:143], v[114:117], v[110:113], v[4:7]
	s_cselect_b64 s[44:45], -1, 0
	s_and_b64 vcc, exec, s[44:45]
	v_mfma_f32_16x16x32_bf16 v[144:147], v[114:117], v[118:121], v[0:3]
	s_nop 2
	ds_read_b128 v[0:3], v64 offset:4096
	ds_read_b128 v[4:7], v64 offset:6144
	v_mfma_f32_16x16x32_bf16 v[148:151], v[114:117], v[128:131], v[16:19]
	s_nop 2
	ds_read_b128 v[16:19], v104
	v_mfma_f32_16x16x32_bf16 v[48:51], v[106:109], v[110:113], v[48:51]
	v_mfma_f32_16x16x32_bf16 v[36:39], v[106:109], v[118:121], v[36:39]
	v_mfma_f32_16x16x32_bf16 v[12:15], v[106:109], v[128:131], v[12:15]
	v_mfma_f32_16x16x32_bf16 v[106:109], v[106:109], v[136:139], v[8:11]
	v_mfma_f32_16x16x32_bf16 v[114:117], v[114:117], v[136:139], v[24:27]
	s_setprio 0
	s_waitcnt lgkmcnt(0)
	v_mfma_f32_16x16x32_bf16 v[156:159], v[0:3], v[118:121], v[28:31]
	v_mfma_f32_16x16x32_bf16 v[160:163], v[0:3], v[128:131], v[32:35]
	v_mfma_f32_16x16x32_bf16 v[44:47], v[0:3], v[136:139], v[44:47]
	v_mfma_f32_16x16x32_bf16 v[52:55], v[4:7], v[118:121], v[52:55]
	v_mfma_f32_16x16x32_bf16 v[56:59], v[4:7], v[128:131], v[56:59]
	ds_read_b128 v[118:121], v105 offset:16384
	ds_read_b128 v[28:31], v104 offset:2048
	ds_read_b128 v[128:131], v105 offset:18432
	v_mfma_f32_16x16x32_bf16 v[60:63], v[4:7], v[136:139], v[60:63]
	ds_read_b128 v[136:139], v105 offset:20480
	ds_read_b128 v[166:169], v105 offset:22528
	v_mfma_f32_16x16x32_bf16 v[152:155], v[0:3], v[110:113], v[20:23]
	s_waitcnt lgkmcnt(0)
	v_mfma_f32_16x16x32_bf16 v[0:3], v[16:19], v[118:121], v[48:51]
	v_mfma_f32_16x16x32_bf16 v[8:11], v[16:19], v[136:139], v[12:15]
	v_mfma_f32_16x16x32_bf16 v[12:15], v[16:19], v[166:169], v[106:109]
	s_nop 0
	ds_read_b128 v[48:51], v104 offset:4096
	s_nop 0
	ds_read_b128 v[106:109], v104 offset:6144
	s_waitcnt vmcnt(0) lgkmcnt(0)
	s_barrier
	s_cbranch_vccnz .Lge4_last0
	s_setprio 1
	v_mfma_f32_16x16x32_bf16 v[110:113], v[4:7], v[110:113], v[40:43]
	s_mov_b32 m0, s59
	v_lshl_add_u64 v[246:247], s[34:35], 0, v[66:67]
	v_lshl_add_u64 v[246:247], v[246:247], 0, s[18:19]
	global_load_lds_dwordx4 v[246:247], off
	v_mfma_f32_16x16x32_bf16 v[4:7], v[16:19], v[128:131], v[36:39]
	s_mov_b32 m0, s60
	v_lshl_add_u64 v[246:247], s[34:35], 0, v[74:75]
	v_lshl_add_u64 v[246:247], v[246:247], 0, s[26:27]
	global_load_lds_dwordx4 v[246:247], off
	v_mfma_f32_16x16x32_bf16 v[16:19], v[28:31], v[118:121], v[140:143]
	s_mov_b32 m0, s61
	v_lshl_add_u64 v[246:247], s[34:35], 0, v[68:69]
	v_lshl_add_u64 v[246:247], v[246:247], 0, s[18:19]
	global_load_lds_dwordx4 v[246:247], off
	v_mfma_f32_16x16x32_bf16 v[20:23], v[28:31], v[128:131], v[144:147]
	s_mov_b32 m0, s62
	v_lshl_add_u64 v[246:247], s[34:35], 0, v[76:77]
	v_lshl_add_u64 v[246:247], v[246:247], 0, s[26:27]
	global_load_lds_dwordx4 v[246:247], off
	v_mfma_f32_16x16x32_bf16 v[24:27], v[28:31], v[136:139], v[148:151]
	s_mov_b32 m0, s63
	v_lshl_add_u64 v[246:247], s[34:35], 0, v[70:71]
	v_lshl_add_u64 v[246:247], v[246:247], 0, s[18:19]
	global_load_lds_dwordx4 v[246:247], off
	v_mfma_f32_16x16x32_bf16 v[28:31], v[28:31], v[166:169], v[114:117]
	s_mov_b32 m0, s64
	v_lshl_add_u64 v[246:247], s[34:35], 0, v[78:79]
	v_lshl_add_u64 v[246:247], v[246:247], 0, s[26:27]
	global_load_lds_dwordx4 v[246:247], off
	s_waitcnt lgkmcnt(0)
	v_mfma_f32_16x16x32_bf16 v[32:35], v[48:51], v[118:121], v[152:155]
	s_mov_b32 m0, s65
	v_lshl_add_u64 v[246:247], s[34:35], 0, v[72:73]
	v_lshl_add_u64 v[246:247], v[246:247], 0, s[18:19]
	global_load_lds_dwordx4 v[246:247], off
	v_mfma_f32_16x16x32_bf16 v[36:39], v[48:51], v[128:131], v[156:159]
	s_mov_b32 m0, s68
	v_lshl_add_u64 v[246:247], s[34:35], 0, v[80:81]
	v_lshl_add_u64 v[246:247], v[246:247], 0, s[26:27]
	global_load_lds_dwordx4 v[246:247], off
	v_mfma_f32_16x16x32_bf16 v[40:43], v[48:51], v[136:139], v[160:163]
	v_mfma_f32_16x16x32_bf16 v[44:47], v[48:51], v[166:169], v[44:47]
	v_mfma_f32_16x16x32_bf16 v[48:51], v[106:109], v[118:121], v[110:113]
	v_mfma_f32_16x16x32_bf16 v[52:55], v[106:109], v[128:131], v[52:55]
	v_mfma_f32_16x16x32_bf16 v[56:59], v[106:109], v[136:139], v[56:59]
	v_mfma_f32_16x16x32_bf16 v[60:63], v[106:109], v[166:169], v[60:63]
	s_branch .LBB0_959

; #define GBAR() do { asm volatile("s_waitcnt vmcnt(0) lgkmcnt(0)" ::: "memory"); __builtin_amdgcn_s_barrier(); } while (0)
; template <int EPI, bool GUARD>
; DEVI void gemm_tile(const Params& p, const bf16_t* __restrict__ A, int lda, const bf16_t* __restrict__ Bt, int ldb, int K,
;                           int row_base, int row_lo, int row_hi, int tile_n, int layer, int which, char* lds) {
;     ...
;   const int swz = c16 >> 1;
;   int koff[2];
; #pragma unroll
;   for (int ks = 0; ks < 2; ++ks) koff[ks] = ((ks * 4 + q4) ^ swz) << 4;
;   const int arow = (wr * 64 + c16) * 128, brow = 16384 + (wc * 64 + c16) * 128;
;     ...
;   GISSUE(0, 0); GBAR();
;   for (int k0 = 0; k0 < K; k0 += 128) {
;     GISSUE(k0 + 64, 1);
;     KSTEPS(0);
;     GBAR();
;     if (k0 + 128 < K) GISSUE(k0 + 128, 0);
;     KSTEPS(1);
;     GBAR();
;   }
.LBB0_1131:
	ds_read_b128 v[82:85], v64 offset:32768
	ds_read_b128 v[86:89], v107 offset:49152
	ds_read_b128 v[90:93], v64 offset:34816
	ds_read_b128 v[94:97], v107 offset:51200
	ds_read_b128 v[110:113], v107 offset:53248
	ds_read_b128 v[114:117], v107 offset:55296
	s_addk_i32 s52, 0x80
	s_waitcnt lgkmcnt(0)
	v_mfma_f32_16x16x32_bf16 v[0:3], v[82:85], v[86:89], v[0:3]
	s_add_u32 s18, s18, 0x100
	s_addc_u32 s19, s19, 0
	s_andn2_b64 vcc, exec, s[26:27]
	v_mfma_f32_16x16x32_bf16 v[4:7], v[82:85], v[94:97], v[4:7]
	v_mfma_f32_16x16x32_bf16 v[8:11], v[82:85], v[110:113], v[8:11]
	v_mfma_f32_16x16x32_bf16 v[12:15], v[82:85], v[114:117], v[12:15]
	v_mfma_f32_16x16x32_bf16 v[16:19], v[90:93], v[86:89], v[16:19]
	v_mfma_f32_16x16x32_bf16 v[20:23], v[90:93], v[94:97], v[20:23]
	v_mfma_f32_16x16x32_bf16 v[24:27], v[90:93], v[110:113], v[24:27]
	v_mfma_f32_16x16x32_bf16 v[28:31], v[90:93], v[114:117], v[28:31]
	s_setprio 0
	ds_read_b128 v[82:85], v64 offset:36864
	ds_read_b128 v[90:93], v64 offset:38912
	s_waitcnt lgkmcnt(0)
	v_mfma_f32_16x16x32_bf16 v[118:121], v[82:85], v[86:89], v[32:35]
	s_nop 2
	ds_read_b128 v[32:35], v108 offset:32768
	v_mfma_f32_16x16x32_bf16 v[122:125], v[82:85], v[94:97], v[36:39]
	v_mfma_f32_16x16x32_bf16 v[126:129], v[82:85], v[110:113], v[40:43]
	v_mfma_f32_16x16x32_bf16 v[82:85], v[82:85], v[114:117], v[44:47]
	v_mfma_f32_16x16x32_bf16 v[86:89], v[90:93], v[86:89], v[48:51]
	v_mfma_f32_16x16x32_bf16 v[94:97], v[90:93], v[94:97], v[52:55]
	v_mfma_f32_16x16x32_bf16 v[110:113], v[90:93], v[110:113], v[56:59]
	v_mfma_f32_16x16x32_bf16 v[90:93], v[90:93], v[114:117], v[60:63]
	ds_read_b128 v[114:117], v109 offset:49152
	ds_read_b128 v[130:133], v108 offset:34816
	ds_read_b128 v[134:137], v109 offset:51200
	ds_read_b128 v[138:141], v109 offset:53248
	ds_read_b128 v[142:145], v109 offset:55296
	s_waitcnt lgkmcnt(0)
	v_mfma_f32_16x16x32_bf16 v[60:63], v[32:35], v[114:117], v[0:3]
	v_mfma_f32_16x16x32_bf16 v[52:55], v[32:35], v[138:141], v[8:11]
	s_nop 1
	ds_read_b128 v[0:3], v108 offset:36864
	ds_read_b128 v[8:11], v108 offset:38912
	s_waitcnt vmcnt(0) lgkmcnt(0)
	s_barrier
	s_cbranch_vccz .Lge5_exit1
	s_setprio 1
	v_mfma_f32_16x16x32_bf16 v[56:59], v[32:35], v[134:137], v[4:7]
	s_mov_b32 m0, s53
	v_lshl_add_u64 v[246:247], s[18:19], 0, v[66:67]
	v_lshl_add_u64 v[246:247], v[246:247], 0, s[2:3]
	global_load_lds_dwordx4 v[246:247], off
	v_mfma_f32_16x16x32_bf16 v[48:51], v[32:35], v[142:145], v[12:15]
	s_mov_b32 m0, s57
	v_lshl_add_u64 v[246:247], s[18:19], 0, v[74:75]
	v_lshl_add_u64 v[246:247], v[246:247], 0, s[4:5]
	global_load_lds_dwordx4 v[246:247], off
	v_mfma_f32_16x16x32_bf16 v[44:47], v[130:133], v[114:117], v[16:19]
	s_mov_b32 m0, s54
	v_lshl_add_u64 v[246:247], s[18:19], 0, v[68:69]
	v_lshl_add_u64 v[246:247], v[246:247], 0, s[2:3]
	global_load_lds_dwordx4 v[246:247], off
	v_mfma_f32_16x16x32_bf16 v[40:43], v[130:133], v[134:137], v[20:23]
	s_mov_b32 m0, s55
	v_lshl_add_u64 v[246:247], s[18:19], 0, v[76:77]
	v_lshl_add_u64 v[246:247], v[246:247], 0, s[4:5]
	global_load_lds_dwordx4 v[246:247], off
	v_mfma_f32_16x16x32_bf16 v[36:39], v[130:133], v[138:141], v[24:27]
	s_mov_b32 m0, s58
	v_lshl_add_u64 v[246:247], s[18:19], 0, v[70:71]
	v_lshl_add_u64 v[246:247], v[246:247], 0, s[2:3]
	global_load_lds_dwordx4 v[246:247], off
	v_mfma_f32_16x16x32_bf16 v[32:35], v[130:133], v[142:145], v[28:31]
	s_mov_b32 m0, s56
	v_lshl_add_u64 v[246:247], s[18:19], 0, v[78:79]
	v_lshl_add_u64 v[246:247], v[246:247], 0, s[4:5]
	global_load_lds_dwordx4 v[246:247], off
	s_waitcnt lgkmcnt(0)
	v_mfma_f32_16x16x32_bf16 v[28:31], v[0:3], v[114:117], v[118:121]
	s_mov_b32 m0, s59
	v_lshl_add_u64 v[246:247], s[18:19], 0, v[72:73]
	v_lshl_add_u64 v[246:247], v[246:247], 0, s[2:3]
	global_load_lds_dwordx4 v[246:247], off
	v_mfma_f32_16x16x32_bf16 v[24:27], v[0:3], v[134:137], v[122:125]
	s_mov_b32 m0, s60
	v_lshl_add_u64 v[246:247], s[18:19], 0, v[80:81]
	v_lshl_add_u64 v[246:247], v[246:247], 0, s[4:5]
	global_load_lds_dwordx4 v[246:247], off
	v_mfma_f32_16x16x32_bf16 v[16:19], v[0:3], v[138:141], v[126:129]
	v_mfma_f32_16x16x32_bf16 v[12:15], v[0:3], v[142:145], v[82:85]
	v_mfma_f32_16x16x32_bf16 v[4:7], v[8:11], v[114:117], v[86:89]
	v_mfma_f32_16x16x32_bf16 v[0:3], v[8:11], v[134:137], v[94:97]
	v_mfma_f32_16x16x32_bf16 v[20:23], v[8:11], v[138:141], v[110:113]
	v_mfma_f32_16x16x32_bf16 v[8:11], v[8:11], v[142:145], v[90:93]
	s_cmpk_gt_u32 s52, 0x37f
	s_cselect_b64 s[26:27], -1, 0
	s_and_b64 vcc, exec, s[26:27]
	s_branch .Lge5_k0

; #define GBAR() do { asm volatile("s_waitcnt vmcnt(0) lgkmcnt(0)" ::: "memory"); __builtin_amdgcn_s_barrier(); } while (0)
; template <int EPI, bool GUARD>
; DEVI void gemm_tile(const Params& p, const bf16_t* __restrict__ A, int lda, const bf16_t* __restrict__ Bt, int ldb, int K,
;                           int row_base, int row_lo, int row_hi, int tile_n, int layer, int which, char* lds) {
;     ...
;   const int swz = c16 >> 1;
;   int koff[2];
; #pragma unroll
;   for (int ks = 0; ks < 2; ++ks) koff[ks] = ((ks * 4 + q4) ^ swz) << 4;
;   const int arow = (wr * 64 + c16) * 128, brow = 16384 + (wc * 64 + c16) * 128;
;     ...
;   GISSUE(0, 0); GBAR();
;   for (int k0 = 0; k0 < K; k0 += 128) {
;     GISSUE(k0 + 64, 1);
;     KSTEPS(0);
;     GBAR();
;     if (k0 + 128 < K) GISSUE(k0 + 128, 0);
;     KSTEPS(1);
;     GBAR();
;   }
.Lge5_k0:
	ds_read_b128 v[110:113], v64
	ds_read_b128 v[114:117], v107 offset:16384
	ds_read_b128 v[118:121], v64 offset:2048
	ds_read_b128 v[122:125], v107 offset:18432
	ds_read_b128 v[126:129], v107 offset:20480
	ds_read_b128 v[130:133], v107 offset:22528
	s_waitcnt lgkmcnt(0)
	v_mfma_f32_16x16x32_bf16 v[60:63], v[110:113], v[114:117], v[60:63]
	v_mfma_f32_16x16x32_bf16 v[56:59], v[110:113], v[122:125], v[56:59]
	v_mfma_f32_16x16x32_bf16 v[52:55], v[110:113], v[126:129], v[52:55]
	v_mfma_f32_16x16x32_bf16 v[48:51], v[110:113], v[130:133], v[48:51]
	v_mfma_f32_16x16x32_bf16 v[44:47], v[118:121], v[114:117], v[44:47]
	v_mfma_f32_16x16x32_bf16 v[40:43], v[118:121], v[122:125], v[40:43]
	v_mfma_f32_16x16x32_bf16 v[36:39], v[118:121], v[126:129], v[36:39]
	v_mfma_f32_16x16x32_bf16 v[32:35], v[118:121], v[130:133], v[32:35]
	s_setprio 0
	ds_read_b128 v[110:113], v64 offset:4096
	ds_read_b128 v[118:121], v64 offset:6144
	s_waitcnt lgkmcnt(0)
	v_mfma_f32_16x16x32_bf16 v[134:137], v[110:113], v[114:117], v[28:31]
	v_mfma_f32_16x16x32_bf16 v[138:141], v[110:113], v[122:125], v[24:27]
	v_mfma_f32_16x16x32_bf16 v[142:145], v[110:113], v[126:129], v[16:19]
	v_mfma_f32_16x16x32_bf16 v[110:113], v[110:113], v[130:133], v[12:15]
	s_nop 2
	ds_read_b128 v[12:15], v108
	v_mfma_f32_16x16x32_bf16 v[114:117], v[118:121], v[114:117], v[4:7]
	v_mfma_f32_16x16x32_bf16 v[122:125], v[118:121], v[122:125], v[0:3]
	v_mfma_f32_16x16x32_bf16 v[126:129], v[118:121], v[126:129], v[20:23]
	v_mfma_f32_16x16x32_bf16 v[118:121], v[118:121], v[130:133], v[8:11]
	ds_read_b128 v[130:133], v109 offset:16384
	ds_read_b128 v[28:31], v108 offset:2048
	ds_read_b128 v[146:149], v109 offset:18432
	s_waitcnt lgkmcnt(0)
	v_mfma_f32_16x16x32_bf16 v[0:3], v[12:15], v[130:133], v[60:63]
	v_mfma_f32_16x16x32_bf16 v[4:7], v[12:15], v[146:149], v[56:59]
	s_nop 2
	ds_read_b128 v[56:59], v109 offset:20480
	ds_read_b128 v[60:63], v109 offset:22528
	v_mfma_f32_16x16x32_bf16 v[16:19], v[28:31], v[130:133], v[44:47]
	s_nop 2
	ds_read_b128 v[44:47], v108 offset:4096
	ds_read_b128 v[150:153], v108 offset:6144
	s_waitcnt vmcnt(0) lgkmcnt(0)
	s_barrier
	s_cbranch_vccnz .Lge5_last0
	s_setprio 1
	s_waitcnt lgkmcnt(0)
	v_mfma_f32_16x16x32_bf16 v[8:11], v[12:15], v[56:59], v[52:55]
	s_mov_b32 m0, s40
	v_lshl_add_u64 v[246:247], s[18:19], 0, v[66:67]
	v_lshl_add_u64 v[246:247], v[246:247], 0, s[6:7]
	global_load_lds_dwordx4 v[246:247], off
	v_mfma_f32_16x16x32_bf16 v[12:15], v[12:15], v[60:63], v[48:51]
	s_mov_b32 m0, s41
	v_lshl_add_u64 v[246:247], s[18:19], 0, v[74:75]
	v_lshl_add_u64 v[246:247], v[246:247], 0, s[8:9]
	global_load_lds_dwordx4 v[246:247], off
	v_mfma_f32_16x16x32_bf16 v[20:23], v[28:31], v[146:149], v[40:43]
	s_mov_b32 m0, s42
	v_lshl_add_u64 v[246:247], s[18:19], 0, v[68:69]
	v_lshl_add_u64 v[246:247], v[246:247], 0, s[6:7]
	global_load_lds_dwordx4 v[246:247], off
	v_mfma_f32_16x16x32_bf16 v[24:27], v[28:31], v[56:59], v[36:39]
	s_mov_b32 m0, s43
	v_lshl_add_u64 v[246:247], s[18:19], 0, v[76:77]
	v_lshl_add_u64 v[246:247], v[246:247], 0, s[8:9]
	global_load_lds_dwordx4 v[246:247], off
	v_mfma_f32_16x16x32_bf16 v[28:31], v[28:31], v[60:63], v[32:35]
	s_mov_b32 m0, s44
	v_lshl_add_u64 v[246:247], s[18:19], 0, v[70:71]
	v_lshl_add_u64 v[246:247], v[246:247], 0, s[6:7]
	global_load_lds_dwordx4 v[246:247], off
	v_mfma_f32_16x16x32_bf16 v[32:35], v[44:47], v[130:133], v[134:137]
	s_mov_b32 m0, s45
	v_lshl_add_u64 v[246:247], s[18:19], 0, v[78:79]
	v_lshl_add_u64 v[246:247], v[246:247], 0, s[8:9]
	global_load_lds_dwordx4 v[246:247], off
	v_mfma_f32_16x16x32_bf16 v[36:39], v[44:47], v[146:149], v[138:141]
	s_mov_b32 m0, s46
	v_lshl_add_u64 v[246:247], s[18:19], 0, v[72:73]
	v_lshl_add_u64 v[246:247], v[246:247], 0, s[6:7]
	global_load_lds_dwordx4 v[246:247], off
	v_mfma_f32_16x16x32_bf16 v[40:43], v[44:47], v[56:59], v[142:145]
	s_mov_b32 m0, s47
	v_lshl_add_u64 v[246:247], s[18:19], 0, v[80:81]
	v_lshl_add_u64 v[246:247], v[246:247], 0, s[8:9]
	global_load_lds_dwordx4 v[246:247], off
	v_mfma_f32_16x16x32_bf16 v[44:47], v[44:47], v[60:63], v[110:113]
	v_mfma_f32_16x16x32_bf16 v[48:51], v[150:153], v[130:133], v[114:117]
	v_mfma_f32_16x16x32_bf16 v[52:55], v[150:153], v[146:149], v[122:125]
	v_mfma_f32_16x16x32_bf16 v[56:59], v[150:153], v[56:59], v[126:129]
	v_mfma_f32_16x16x32_bf16 v[60:63], v[150:153], v[60:63], v[118:121]
	s_branch .LBB0_1131

; #define GBAR() do { asm volatile("s_waitcnt vmcnt(0) lgkmcnt(0)" ::: "memory"); __builtin_amdgcn_s_barrier(); } while (0)
; template <int EPI, bool GUARD>
; DEVI void gemm_tile(const Params& p, const bf16_t* __restrict__ A, int lda, const bf16_t* __restrict__ Bt, int ldb, int K,
;                           int row_base, int row_lo, int row_hi, int tile_n, int layer, int which, char* lds) {
;     ...
;   const int swz = c16 >> 1;
;   int koff[2];
; #pragma unroll
;   for (int ks = 0; ks < 2; ++ks) koff[ks] = ((ks * 4 + q4) ^ swz) << 4;
;   const int arow = (wr * 64 + c16) * 128, brow = 16384 + (wc * 64 + c16) * 128;
;     ...
;   GISSUE(0, 0); GBAR();
;   for (int k0 = 0; k0 < K; k0 += 128) {
;     GISSUE(k0 + 64, 1);
;     KSTEPS(0);
;     GBAR();
;     if (k0 + 128 < K) GISSUE(k0 + 128, 0);
;     KSTEPS(1);
;     GBAR();
;   }
.LBB0_1258:
	ds_read_b128 v[82:85], v64 offset:32768
	ds_read_b128 v[86:89], v112 offset:49152
	ds_read_b128 v[90:93], v64 offset:34816
	ds_read_b128 v[94:97], v112 offset:51200
	ds_read_b128 v[116:119], v112 offset:53248
	ds_read_b128 v[120:123], v112 offset:55296
	s_addk_i32 s51, 0x80
	s_waitcnt lgkmcnt(0)
	v_mfma_f32_16x16x32_bf16 v[0:3], v[82:85], v[86:89], v[0:3]
	s_add_u32 s2, s2, 0x100
	s_addc_u32 s3, s3, 0
	s_and_b64 vcc, exec, s[4:5]
	v_mfma_f32_16x16x32_bf16 v[4:7], v[82:85], v[94:97], v[4:7]
	v_mfma_f32_16x16x32_bf16 v[8:11], v[82:85], v[116:119], v[8:11]
	v_mfma_f32_16x16x32_bf16 v[12:15], v[82:85], v[120:123], v[12:15]
	v_mfma_f32_16x16x32_bf16 v[82:85], v[90:93], v[86:89], v[16:19]
	v_mfma_f32_16x16x32_bf16 v[20:23], v[90:93], v[94:97], v[20:23]
	v_mfma_f32_16x16x32_bf16 v[24:27], v[90:93], v[116:119], v[24:27]
	v_mfma_f32_16x16x32_bf16 v[28:31], v[90:93], v[120:123], v[28:31]
	s_setprio 0
	ds_read_b128 v[16:19], v64 offset:36864
	ds_read_b128 v[90:93], v64 offset:38912
	s_waitcnt lgkmcnt(0)
	v_mfma_f32_16x16x32_bf16 v[124:127], v[16:19], v[86:89], v[32:35]
	v_mfma_f32_16x16x32_bf16 v[36:39], v[16:19], v[94:97], v[36:39]
	v_mfma_f32_16x16x32_bf16 v[40:43], v[16:19], v[116:119], v[40:43]
	v_mfma_f32_16x16x32_bf16 v[44:47], v[16:19], v[120:123], v[44:47]
	ds_read_b128 v[16:19], v113 offset:32768
	v_mfma_f32_16x16x32_bf16 v[86:89], v[90:93], v[86:89], v[48:51]
	v_mfma_f32_16x16x32_bf16 v[52:55], v[90:93], v[94:97], v[52:55]
	v_mfma_f32_16x16x32_bf16 v[56:59], v[90:93], v[116:119], v[56:59]
	v_mfma_f32_16x16x32_bf16 v[60:63], v[90:93], v[120:123], v[60:63]
	ds_read_b128 v[90:93], v114 offset:49152
	ds_read_b128 v[32:35], v113 offset:34816
	ds_read_b128 v[94:97], v114 offset:51200
	ds_read_b128 v[116:119], v114 offset:53248
	ds_read_b128 v[120:123], v114 offset:55296
	s_waitcnt lgkmcnt(0)
	v_mfma_f32_16x16x32_bf16 v[0:3], v[16:19], v[90:93], v[0:3]
	v_mfma_f32_16x16x32_bf16 v[4:7], v[16:19], v[94:97], v[4:7]
	v_mfma_f32_16x16x32_bf16 v[8:11], v[16:19], v[116:119], v[8:11]
	v_mfma_f32_16x16x32_bf16 v[16:19], v[16:19], v[120:123], v[12:15]
	v_mfma_f32_16x16x32_bf16 v[12:15], v[32:35], v[90:93], v[82:85]
	ds_read_b128 v[48:51], v113 offset:36864
	s_nop 1
	ds_read_b128 v[82:85], v113 offset:38912
	s_waitcnt vmcnt(0) lgkmcnt(0)
	s_barrier
	s_cbranch_vccnz .Lge6_exit1
	s_setprio 1
	v_mfma_f32_16x16x32_bf16 v[20:23], v[32:35], v[94:97], v[20:23]
	s_add_i32 m0, s52, 0x8000
	v_lshl_add_u64 v[246:247], s[2:3], 0, v[66:67]
	v_lshl_add_u64 v[246:247], v[246:247], 0, s[18:19]
	global_load_lds_dwordx4 v[246:247], off
	v_mfma_f32_16x16x32_bf16 v[24:27], v[32:35], v[116:119], v[24:27]
	s_add_i32 m0, s52, 0xc000
	v_lshl_add_u64 v[246:247], s[2:3], 0, v[74:75]
	v_lshl_add_u64 v[246:247], v[246:247], 0, s[26:27]
	global_load_lds_dwordx4 v[246:247], off
	v_mfma_f32_16x16x32_bf16 v[32:35], v[32:35], v[120:123], v[28:31]
	s_add_i32 m0, s52, 0x8400
	v_lshl_add_u64 v[246:247], s[2:3], 0, v[68:69]
	v_lshl_add_u64 v[246:247], v[246:247], 0, s[18:19]
	global_load_lds_dwordx4 v[246:247], off
	s_waitcnt lgkmcnt(0)
	v_mfma_f32_16x16x32_bf16 v[28:31], v[48:51], v[90:93], v[124:127]
	s_add_i32 m0, s52, 0xc400
	v_lshl_add_u64 v[246:247], s[2:3], 0, v[76:77]
	v_lshl_add_u64 v[246:247], v[246:247], 0, s[26:27]
	global_load_lds_dwordx4 v[246:247], off
	v_mfma_f32_16x16x32_bf16 v[36:39], v[48:51], v[94:97], v[36:39]
	s_add_i32 m0, s52, 0x8800
	v_lshl_add_u64 v[246:247], s[2:3], 0, v[70:71]
	v_lshl_add_u64 v[246:247], v[246:247], 0, s[18:19]
	global_load_lds_dwordx4 v[246:247], off
	v_mfma_f32_16x16x32_bf16 v[40:43], v[48:51], v[116:119], v[40:43]
	s_add_i32 m0, s52, 0xc800
	v_lshl_add_u64 v[246:247], s[2:3], 0, v[78:79]
	v_lshl_add_u64 v[246:247], v[246:247], 0, s[26:27]
	global_load_lds_dwordx4 v[246:247], off
	v_mfma_f32_16x16x32_bf16 v[48:51], v[48:51], v[120:123], v[44:47]
	s_add_i32 m0, s58, 0x8000
	v_lshl_add_u64 v[246:247], s[2:3], 0, v[72:73]
	v_lshl_add_u64 v[246:247], v[246:247], 0, s[18:19]
	global_load_lds_dwordx4 v[246:247], off
	v_mfma_f32_16x16x32_bf16 v[44:47], v[82:85], v[90:93], v[86:89]
	s_add_i32 m0, s58, 0xc000
	v_lshl_add_u64 v[246:247], s[2:3], 0, v[80:81]
	v_lshl_add_u64 v[246:247], v[246:247], 0, s[26:27]
	global_load_lds_dwordx4 v[246:247], off
	v_mfma_f32_16x16x32_bf16 v[52:55], v[82:85], v[94:97], v[52:55]
	v_mfma_f32_16x16x32_bf16 v[56:59], v[82:85], v[116:119], v[56:59]
	v_mfma_f32_16x16x32_bf16 v[60:63], v[82:85], v[120:123], v[60:63]
	s_cmpk_gt_u32 s51, 0x37f
	s_branch .Lge6_k0

; #define GBAR() do { asm volatile("s_waitcnt vmcnt(0) lgkmcnt(0)" ::: "memory"); __builtin_amdgcn_s_barrier(); } while (0)
; template <int EPI, bool GUARD>
; DEVI void gemm_tile(const Params& p, const bf16_t* __restrict__ A, int lda, const bf16_t* __restrict__ Bt, int ldb, int K,
;                           int row_base, int row_lo, int row_hi, int tile_n, int layer, int which, char* lds) {
;     ...
;   const int swz = c16 >> 1;
;   int koff[2];
; #pragma unroll
;   for (int ks = 0; ks < 2; ++ks) koff[ks] = ((ks * 4 + q4) ^ swz) << 4;
;   const int arow = (wr * 64 + c16) * 128, brow = 16384 + (wc * 64 + c16) * 128;
;     ...
;   GISSUE(0, 0); GBAR();
;   for (int k0 = 0; k0 < K; k0 += 128) {
;     GISSUE(k0 + 64, 1);
;     KSTEPS(0);
;     GBAR();
;     if (k0 + 128 < K) GISSUE(k0 + 128, 0);
;     KSTEPS(1);
;     GBAR();
;   }
.Lge6_k0:
	ds_read_b128 v[116:119], v64
	ds_read_b128 v[120:123], v112 offset:16384
	ds_read_b128 v[124:127], v64 offset:2048
	ds_read_b128 v[128:131], v112 offset:18432
	ds_read_b128 v[132:135], v112 offset:20480
	ds_read_b128 v[136:139], v112 offset:22528
	s_waitcnt lgkmcnt(0)
	v_mfma_f32_16x16x32_bf16 v[0:3], v[116:119], v[120:123], v[0:3]
	s_cselect_b64 s[4:5], -1, 0
	s_and_b64 vcc, exec, s[4:5]
	v_mfma_f32_16x16x32_bf16 v[4:7], v[116:119], v[128:131], v[4:7]
	v_mfma_f32_16x16x32_bf16 v[8:11], v[116:119], v[132:135], v[8:11]
	v_mfma_f32_16x16x32_bf16 v[16:19], v[116:119], v[136:139], v[16:19]
	v_mfma_f32_16x16x32_bf16 v[116:119], v[124:127], v[120:123], v[12:15]
	v_mfma_f32_16x16x32_bf16 v[20:23], v[124:127], v[128:131], v[20:23]
	v_mfma_f32_16x16x32_bf16 v[24:27], v[124:127], v[132:135], v[24:27]
	v_mfma_f32_16x16x32_bf16 v[32:35], v[124:127], v[136:139], v[32:35]
	s_setprio 0
	ds_read_b128 v[12:15], v64 offset:4096
	ds_read_b128 v[124:127], v64 offset:6144
	s_waitcnt lgkmcnt(0)
	v_mfma_f32_16x16x32_bf16 v[140:143], v[12:15], v[120:123], v[28:31]
	v_mfma_f32_16x16x32_bf16 v[36:39], v[12:15], v[128:131], v[36:39]
	v_mfma_f32_16x16x32_bf16 v[40:43], v[12:15], v[132:135], v[40:43]
	v_mfma_f32_16x16x32_bf16 v[48:51], v[12:15], v[136:139], v[48:51]
	ds_read_b128 v[12:15], v113
	v_mfma_f32_16x16x32_bf16 v[120:123], v[124:127], v[120:123], v[44:47]
	v_mfma_f32_16x16x32_bf16 v[52:55], v[124:127], v[128:131], v[52:55]
	v_mfma_f32_16x16x32_bf16 v[56:59], v[124:127], v[132:135], v[56:59]
	v_mfma_f32_16x16x32_bf16 v[60:63], v[124:127], v[136:139], v[60:63]
	ds_read_b128 v[124:127], v114 offset:16384
	ds_read_b128 v[28:31], v113 offset:2048
	ds_read_b128 v[128:131], v114 offset:18432
	ds_read_b128 v[132:135], v114 offset:20480
	ds_read_b128 v[136:139], v114 offset:22528
	s_waitcnt lgkmcnt(0)
	v_mfma_f32_16x16x32_bf16 v[0:3], v[12:15], v[124:127], v[0:3]
	v_mfma_f32_16x16x32_bf16 v[4:7], v[12:15], v[128:131], v[4:7]
	v_mfma_f32_16x16x32_bf16 v[8:11], v[12:15], v[132:135], v[8:11]
	v_mfma_f32_16x16x32_bf16 v[12:15], v[12:15], v[136:139], v[16:19]
	v_mfma_f32_16x16x32_bf16 v[16:19], v[28:31], v[124:127], v[116:119]
	ds_read_b128 v[44:47], v113 offset:4096
	s_nop 1
	ds_read_b128 v[116:119], v113 offset:6144
	s_waitcnt vmcnt(0) lgkmcnt(0)
	s_barrier
	s_cbranch_vccnz .Lge6_last0
	s_setprio 1
	v_mfma_f32_16x16x32_bf16 v[20:23], v[28:31], v[128:131], v[20:23]
	s_mov_b32 m0, s52
	v_lshl_add_u64 v[246:247], s[2:3], 0, v[66:67]
	v_lshl_add_u64 v[246:247], v[246:247], 0, s[28:29]
	global_load_lds_dwordx4 v[246:247], off
	v_mfma_f32_16x16x32_bf16 v[24:27], v[28:31], v[132:135], v[24:27]
	s_mov_b32 m0, s53
	v_lshl_add_u64 v[246:247], s[2:3], 0, v[74:75]
	v_lshl_add_u64 v[246:247], v[246:247], 0, s[30:31]
	global_load_lds_dwordx4 v[246:247], off
	v_mfma_f32_16x16x32_bf16 v[28:31], v[28:31], v[136:139], v[32:35]
	s_mov_b32 m0, s54
	v_lshl_add_u64 v[246:247], s[2:3], 0, v[68:69]
	v_lshl_add_u64 v[246:247], v[246:247], 0, s[28:29]
	global_load_lds_dwordx4 v[246:247], off
	s_waitcnt lgkmcnt(0)
	v_mfma_f32_16x16x32_bf16 v[32:35], v[44:47], v[124:127], v[140:143]
	s_mov_b32 m0, s55
	v_lshl_add_u64 v[246:247], s[2:3], 0, v[76:77]
	v_lshl_add_u64 v[246:247], v[246:247], 0, s[30:31]
	global_load_lds_dwordx4 v[246:247], off
	v_mfma_f32_16x16x32_bf16 v[36:39], v[44:47], v[128:131], v[36:39]
	s_mov_b32 m0, s56
	v_lshl_add_u64 v[246:247], s[2:3], 0, v[70:71]
	v_lshl_add_u64 v[246:247], v[246:247], 0, s[28:29]
	global_load_lds_dwordx4 v[246:247], off
	v_mfma_f32_16x16x32_bf16 v[40:43], v[44:47], v[132:135], v[40:43]
	s_mov_b32 m0, s57
	v_lshl_add_u64 v[246:247], s[2:3], 0, v[78:79]
	v_lshl_add_u64 v[246:247], v[246:247], 0, s[30:31]
	global_load_lds_dwordx4 v[246:247], off
	v_mfma_f32_16x16x32_bf16 v[44:47], v[44:47], v[136:139], v[48:51]
	s_mov_b32 m0, s58
	v_lshl_add_u64 v[246:247], s[2:3], 0, v[72:73]
	v_lshl_add_u64 v[246:247], v[246:247], 0, s[28:29]
	global_load_lds_dwordx4 v[246:247], off
	v_mfma_f32_16x16x32_bf16 v[48:51], v[116:119], v[124:127], v[120:123]
	s_mov_b32 m0, s59
	v_lshl_add_u64 v[246:247], s[2:3], 0, v[80:81]
	v_lshl_add_u64 v[246:247], v[246:247], 0, s[30:31]
	global_load_lds_dwordx4 v[246:247], off
	v_mfma_f32_16x16x32_bf16 v[52:55], v[116:119], v[128:131], v[52:55]
	v_mfma_f32_16x16x32_bf16 v[56:59], v[116:119], v[132:135], v[56:59]
	v_mfma_f32_16x16x32_bf16 v[60:63], v[116:119], v[136:139], v[60:63]
	s_branch .LBB0_1258

; #define GBAR() do { asm volatile("s_waitcnt vmcnt(0) lgkmcnt(0)" ::: "memory"); __builtin_amdgcn_s_barrier(); } while (0)
; template <int EPI, bool GUARD>
; DEVI void gemm_tile(const Params& p, const bf16_t* __restrict__ A, int lda, const bf16_t* __restrict__ Bt, int ldb, int K,
;                           int row_base, int row_lo, int row_hi, int tile_n, int layer, int which, char* lds) {
;     ...
;   const int swz = c16 >> 1;
;   int koff[2];
; #pragma unroll
;   for (int ks = 0; ks < 2; ++ks) koff[ks] = ((ks * 4 + q4) ^ swz) << 4;
;   const int arow = (wr * 64 + c16) * 128, brow = 16384 + (wc * 64 + c16) * 128;
;     ...
;   GISSUE(0, 0); GBAR();
;   for (int k0 = 0; k0 < K; k0 += 128) {
;     GISSUE(k0 + 64, 1);
;     KSTEPS(0);
;     GBAR();
;     if (k0 + 128 < K) GISSUE(k0 + 128, 0);
;     KSTEPS(1);
;     GBAR();
;   }
.LBB0_1336:
	ds_read_b128 v[82:85], v64 offset:32768
	ds_read_b128 v[86:89], v107 offset:49152
	ds_read_b128 v[90:93], v64 offset:34816
	ds_read_b128 v[94:97], v107 offset:51200
	ds_read_b128 v[110:113], v107 offset:53248
	ds_read_b128 v[114:117], v107 offset:55296
	s_addk_i32 s44, 0x80
	s_waitcnt lgkmcnt(0)
	v_mfma_f32_16x16x32_bf16 v[0:3], v[82:85], v[86:89], v[0:3]
	s_add_u32 s18, s18, 0x100
	s_addc_u32 s19, s19, 0
	s_andn2_b64 vcc, exec, s[20:21]
	v_mfma_f32_16x16x32_bf16 v[4:7], v[82:85], v[94:97], v[4:7]
	v_mfma_f32_16x16x32_bf16 v[8:11], v[82:85], v[110:113], v[8:11]
	v_mfma_f32_16x16x32_bf16 v[12:15], v[82:85], v[114:117], v[12:15]
	v_mfma_f32_16x16x32_bf16 v[16:19], v[90:93], v[86:89], v[16:19]
	v_mfma_f32_16x16x32_bf16 v[20:23], v[90:93], v[94:97], v[20:23]
	v_mfma_f32_16x16x32_bf16 v[24:27], v[90:93], v[110:113], v[24:27]
	v_mfma_f32_16x16x32_bf16 v[28:31], v[90:93], v[114:117], v[28:31]
	s_setprio 0
	ds_read_b128 v[82:85], v64 offset:36864
	ds_read_b128 v[90:93], v64 offset:38912
	s_waitcnt lgkmcnt(0)
	v_mfma_f32_16x16x32_bf16 v[118:121], v[82:85], v[86:89], v[32:35]
	s_nop 2
	ds_read_b128 v[32:35], v108 offset:32768
	v_mfma_f32_16x16x32_bf16 v[122:125], v[82:85], v[94:97], v[36:39]
	v_mfma_f32_16x16x32_bf16 v[126:129], v[82:85], v[110:113], v[40:43]
	v_mfma_f32_16x16x32_bf16 v[82:85], v[82:85], v[114:117], v[44:47]
	v_mfma_f32_16x16x32_bf16 v[86:89], v[90:93], v[86:89], v[48:51]
	v_mfma_f32_16x16x32_bf16 v[94:97], v[90:93], v[94:97], v[52:55]
	v_mfma_f32_16x16x32_bf16 v[110:113], v[90:93], v[110:113], v[56:59]
	v_mfma_f32_16x16x32_bf16 v[90:93], v[90:93], v[114:117], v[60:63]
	ds_read_b128 v[114:117], v109 offset:49152
	ds_read_b128 v[130:133], v108 offset:34816
	ds_read_b128 v[134:137], v109 offset:51200
	ds_read_b128 v[138:141], v109 offset:53248
	ds_read_b128 v[142:145], v109 offset:55296
	s_waitcnt lgkmcnt(0)
	v_mfma_f32_16x16x32_bf16 v[60:63], v[32:35], v[114:117], v[0:3]
	v_mfma_f32_16x16x32_bf16 v[52:55], v[32:35], v[138:141], v[8:11]
	s_nop 1
	ds_read_b128 v[0:3], v108 offset:36864
	ds_read_b128 v[8:11], v108 offset:38912
	s_waitcnt vmcnt(0) lgkmcnt(0)
	s_barrier
	s_cbranch_vccz .Lge7_exit1
	s_setprio 1
	v_mfma_f32_16x16x32_bf16 v[56:59], v[32:35], v[134:137], v[4:7]
	s_mov_b32 m0, s45
	v_lshl_add_u64 v[246:247], s[18:19], 0, v[66:67]
	v_lshl_add_u64 v[246:247], v[246:247], 0, s[2:3]
	global_load_lds_dwordx4 v[246:247], off
	v_mfma_f32_16x16x32_bf16 v[48:51], v[32:35], v[142:145], v[12:15]
	s_mov_b32 m0, s50
	v_lshl_add_u64 v[246:247], s[18:19], 0, v[74:75]
	v_lshl_add_u64 v[246:247], v[246:247], 0, s[4:5]
	global_load_lds_dwordx4 v[246:247], off
	v_mfma_f32_16x16x32_bf16 v[44:47], v[130:133], v[114:117], v[16:19]
	s_mov_b32 m0, s46
	v_lshl_add_u64 v[246:247], s[18:19], 0, v[68:69]
	v_lshl_add_u64 v[246:247], v[246:247], 0, s[2:3]
	global_load_lds_dwordx4 v[246:247], off
	v_mfma_f32_16x16x32_bf16 v[40:43], v[130:133], v[134:137], v[20:23]
	s_mov_b32 m0, s47
	v_lshl_add_u64 v[246:247], s[18:19], 0, v[76:77]
	v_lshl_add_u64 v[246:247], v[246:247], 0, s[4:5]
	global_load_lds_dwordx4 v[246:247], off
	v_mfma_f32_16x16x32_bf16 v[36:39], v[130:133], v[138:141], v[24:27]
	s_mov_b32 m0, s48
	v_lshl_add_u64 v[246:247], s[18:19], 0, v[70:71]
	v_lshl_add_u64 v[246:247], v[246:247], 0, s[2:3]
	global_load_lds_dwordx4 v[246:247], off
	v_mfma_f32_16x16x32_bf16 v[32:35], v[130:133], v[142:145], v[28:31]
	s_mov_b32 m0, s49
	v_lshl_add_u64 v[246:247], s[18:19], 0, v[78:79]
	v_lshl_add_u64 v[246:247], v[246:247], 0, s[4:5]
	global_load_lds_dwordx4 v[246:247], off
	s_waitcnt lgkmcnt(0)
	v_mfma_f32_16x16x32_bf16 v[28:31], v[0:3], v[114:117], v[118:121]
	s_mov_b32 m0, s51
	v_lshl_add_u64 v[246:247], s[18:19], 0, v[72:73]
	v_lshl_add_u64 v[246:247], v[246:247], 0, s[2:3]
	global_load_lds_dwordx4 v[246:247], off
	v_mfma_f32_16x16x32_bf16 v[24:27], v[0:3], v[134:137], v[122:125]
	s_mov_b32 m0, s52
	v_lshl_add_u64 v[246:247], s[18:19], 0, v[80:81]
	v_lshl_add_u64 v[246:247], v[246:247], 0, s[4:5]
	global_load_lds_dwordx4 v[246:247], off
	v_mfma_f32_16x16x32_bf16 v[16:19], v[0:3], v[138:141], v[126:129]
	v_mfma_f32_16x16x32_bf16 v[12:15], v[0:3], v[142:145], v[82:85]
	v_mfma_f32_16x16x32_bf16 v[4:7], v[8:11], v[114:117], v[86:89]
	v_mfma_f32_16x16x32_bf16 v[0:3], v[8:11], v[134:137], v[94:97]
	v_mfma_f32_16x16x32_bf16 v[20:23], v[8:11], v[138:141], v[110:113]
	v_mfma_f32_16x16x32_bf16 v[8:11], v[8:11], v[142:145], v[90:93]
	s_cmpk_gt_u32 s44, 0xa7f
	s_cselect_b64 s[20:21], -1, 0
	s_and_b64 vcc, exec, s[20:21]
	s_branch .Lge7_k0

; #define GBAR() do { asm volatile("s_waitcnt vmcnt(0) lgkmcnt(0)" ::: "memory"); __builtin_amdgcn_s_barrier(); } while (0)
; template <int EPI, bool GUARD>
; DEVI void gemm_tile(const Params& p, const bf16_t* __restrict__ A, int lda, const bf16_t* __restrict__ Bt, int ldb, int K,
;                           int row_base, int row_lo, int row_hi, int tile_n, int layer, int which, char* lds) {
;     ...
;   const int swz = c16 >> 1;
;   int koff[2];
; #pragma unroll
;   for (int ks = 0; ks < 2; ++ks) koff[ks] = ((ks * 4 + q4) ^ swz) << 4;
;   const int arow = (wr * 64 + c16) * 128, brow = 16384 + (wc * 64 + c16) * 128;
;     ...
;   GISSUE(0, 0); GBAR();
;   for (int k0 = 0; k0 < K; k0 += 128) {
;     GISSUE(k0 + 64, 1);
;     KSTEPS(0);
;     GBAR();
;     if (k0 + 128 < K) GISSUE(k0 + 128, 0);
;     KSTEPS(1);
;     GBAR();
;   }
.Lge7_k0:
	ds_read_b128 v[110:113], v64
	ds_read_b128 v[114:117], v107 offset:16384
	ds_read_b128 v[118:121], v64 offset:2048
	ds_read_b128 v[122:125], v107 offset:18432
	ds_read_b128 v[126:129], v107 offset:20480
	ds_read_b128 v[130:133], v107 offset:22528
	s_waitcnt lgkmcnt(0)
	v_mfma_f32_16x16x32_bf16 v[60:63], v[110:113], v[114:117], v[60:63]
	v_mfma_f32_16x16x32_bf16 v[56:59], v[110:113], v[122:125], v[56:59]
	v_mfma_f32_16x16x32_bf16 v[52:55], v[110:113], v[126:129], v[52:55]
	v_mfma_f32_16x16x32_bf16 v[48:51], v[110:113], v[130:133], v[48:51]
	v_mfma_f32_16x16x32_bf16 v[44:47], v[118:121], v[114:117], v[44:47]
	v_mfma_f32_16x16x32_bf16 v[40:43], v[118:121], v[122:125], v[40:43]
	v_mfma_f32_16x16x32_bf16 v[36:39], v[118:121], v[126:129], v[36:39]
	v_mfma_f32_16x16x32_bf16 v[32:35], v[118:121], v[130:133], v[32:35]
	s_setprio 0
	ds_read_b128 v[110:113], v64 offset:4096
	ds_read_b128 v[118:121], v64 offset:6144
	s_waitcnt lgkmcnt(0)
	v_mfma_f32_16x16x32_bf16 v[134:137], v[110:113], v[114:117], v[28:31]
	v_mfma_f32_16x16x32_bf16 v[138:141], v[110:113], v[122:125], v[24:27]
	v_mfma_f32_16x16x32_bf16 v[142:145], v[110:113], v[126:129], v[16:19]
	v_mfma_f32_16x16x32_bf16 v[110:113], v[110:113], v[130:133], v[12:15]
	s_nop 2
	ds_read_b128 v[12:15], v108
	v_mfma_f32_16x16x32_bf16 v[114:117], v[118:121], v[114:117], v[4:7]
	v_mfma_f32_16x16x32_bf16 v[122:125], v[118:121], v[122:125], v[0:3]
	v_mfma_f32_16x16x32_bf16 v[126:129], v[118:121], v[126:129], v[20:23]
	v_mfma_f32_16x16x32_bf16 v[118:121], v[118:121], v[130:133], v[8:11]
	ds_read_b128 v[130:133], v109 offset:16384
	ds_read_b128 v[28:31], v108 offset:2048
	ds_read_b128 v[146:149], v109 offset:18432
	s_waitcnt lgkmcnt(0)
	v_mfma_f32_16x16x32_bf16 v[0:3], v[12:15], v[130:133], v[60:63]
	v_mfma_f32_16x16x32_bf16 v[4:7], v[12:15], v[146:149], v[56:59]
	s_nop 2
	ds_read_b128 v[56:59], v109 offset:20480
	ds_read_b128 v[60:63], v109 offset:22528
	v_mfma_f32_16x16x32_bf16 v[16:19], v[28:31], v[130:133], v[44:47]
	s_nop 2
	ds_read_b128 v[44:47], v108 offset:4096
	ds_read_b128 v[150:153], v108 offset:6144
	s_waitcnt vmcnt(0) lgkmcnt(0)
	s_barrier
	s_cbranch_vccnz .Lge7_last0
	s_setprio 1
	s_waitcnt lgkmcnt(0)
	v_mfma_f32_16x16x32_bf16 v[8:11], v[12:15], v[56:59], v[52:55]
	s_mov_b32 m0, s36
	v_lshl_add_u64 v[246:247], s[18:19], 0, v[66:67]
	v_lshl_add_u64 v[246:247], v[246:247], 0, s[6:7]
	global_load_lds_dwordx4 v[246:247], off
	v_mfma_f32_16x16x32_bf16 v[12:15], v[12:15], v[60:63], v[48:51]
	s_mov_b32 m0, s37
	v_lshl_add_u64 v[246:247], s[18:19], 0, v[74:75]
	v_lshl_add_u64 v[246:247], v[246:247], 0, s[8:9]
	global_load_lds_dwordx4 v[246:247], off
	v_mfma_f32_16x16x32_bf16 v[20:23], v[28:31], v[146:149], v[40:43]
	s_mov_b32 m0, s38
	v_lshl_add_u64 v[246:247], s[18:19], 0, v[68:69]
	v_lshl_add_u64 v[246:247], v[246:247], 0, s[6:7]
	global_load_lds_dwordx4 v[246:247], off
	v_mfma_f32_16x16x32_bf16 v[24:27], v[28:31], v[56:59], v[36:39]
	s_mov_b32 m0, s39
	v_lshl_add_u64 v[246:247], s[18:19], 0, v[76:77]
	v_lshl_add_u64 v[246:247], v[246:247], 0, s[8:9]
	global_load_lds_dwordx4 v[246:247], off
	v_mfma_f32_16x16x32_bf16 v[28:31], v[28:31], v[60:63], v[32:35]
	s_mov_b32 m0, s40
	v_lshl_add_u64 v[246:247], s[18:19], 0, v[70:71]
	v_lshl_add_u64 v[246:247], v[246:247], 0, s[6:7]
	global_load_lds_dwordx4 v[246:247], off
	v_mfma_f32_16x16x32_bf16 v[32:35], v[44:47], v[130:133], v[134:137]
	s_mov_b32 m0, s41
	v_lshl_add_u64 v[246:247], s[18:19], 0, v[78:79]
	v_lshl_add_u64 v[246:247], v[246:247], 0, s[8:9]
	global_load_lds_dwordx4 v[246:247], off
	v_mfma_f32_16x16x32_bf16 v[36:39], v[44:47], v[146:149], v[138:141]
	s_mov_b32 m0, s42
	v_lshl_add_u64 v[246:247], s[18:19], 0, v[72:73]
	v_lshl_add_u64 v[246:247], v[246:247], 0, s[6:7]
	global_load_lds_dwordx4 v[246:247], off
	v_mfma_f32_16x16x32_bf16 v[40:43], v[44:47], v[56:59], v[142:145]
	s_mov_b32 m0, s43
	v_lshl_add_u64 v[246:247], s[18:19], 0, v[80:81]
	v_lshl_add_u64 v[246:247], v[246:247], 0, s[8:9]
	global_load_lds_dwordx4 v[246:247], off
	v_mfma_f32_16x16x32_bf16 v[44:47], v[44:47], v[60:63], v[110:113]
	v_mfma_f32_16x16x32_bf16 v[48:51], v[150:153], v[130:133], v[114:117]
	v_mfma_f32_16x16x32_bf16 v[52:55], v[150:153], v[146:149], v[122:125]
	v_mfma_f32_16x16x32_bf16 v[56:59], v[150:153], v[56:59], v[126:129]
	v_mfma_f32_16x16x32_bf16 v[60:63], v[150:153], v[60:63], v[118:121]
	s_branch .LBB0_1336
